# init phase rewritten with row loads one row ahead; weight-conversion loop head waits counted so they do not wait for the output stores
# baseline (speedup 1.0000x reference)
; #define LAS __attribute__((address_space(3)))
; __device__ __forceinline__ int opaque_tid(int wv) { asm volatile("" : "+s"(wv)); unsigned z = 0u; asm volatile("" : "+v"(z)); const int l = __builtin_amdgcn_mbcnt_hi(~0u, __builtin_amdgcn_mbcnt_lo(~0u, z)); return (wv << 6) | l; }
; __device__ __forceinline__ void convert_weight(int wv, const float* __restrict__ src, int ldsrc, int Ksrc, bf16_t* dst, int ldd, int koff, int ntn, const float* kscale, int mode, LAS float* tile, int pidx, int pcnt) {
;     const int tid = opaque_tid(wv); const int ntk = Ksrc / 128; const int total = ntn * ntk; const int G = pcnt;
;     const int kk0 = tid >> 4, n4 = (tid & 15) * 4;
;     f32x4 v[4]; float ks[4];
;     auto prefetch = [&](int t) {
;         const int tn = t % ntn, tk = t / ntn; const int n0 = tn * 64, k0 = tk * 128;
;         int scol = n0, nvalid = 64;
;         if (mode == 1) { if (n0 < 5632) scol = n0; else if (n0 < 13312) scol = n0 + 8; else if (n0 == 13312) { scol = 5632; nvalid = 8; } else { scol = 0; nvalid = 0; } }
; #pragma unroll
;         for (int i = 0; i < 4; ++i) { const int kk = kk0 + i * 32; v[i] = (f32x4){0.f, 0.f, 0.f, 0.f};
;             if (n4 < nvalid) v[i] = *(const f32x4*)(src + (size_t)(k0 + kk) * ldsrc + scol + n4);
;             ks[i] = kscale ? kscale[k0 + kk] : 1.0f; }
;     };
;     int t = pidx; int buf = 0;
;     if (t < total) prefetch(t);
;     for (; t < total; t += G) {
;         LAS float* tl = tile + buf * (128 * 65);
.LBB0_30:
	v_lshlrev_b32_e32 v11, 4, v11
	s_waitcnt lgkmcnt(0)
	s_add_u32 s14, s4, 0x23100000
	v_and_b32_e32 v30, 0x70, v11
	s_movk_i32 s16, 0x104
	s_addc_u32 s15, s5, 0
	v_cmp_gt_u32_e64 s[4:5], 8, v22
	v_mov_b32_e32 v10, 0
	v_ashrrev_i32_e32 v27, 3, v13
	v_mul_u32_u24_e32 v35, 0x104, v30
	v_mul_lo_u32 v38, v24, s16
	s_lshl_b32 s30, s26, 6
	s_lshl_b32 s27, s48, 6
	s_mov_b32 s28, 0
	s_mov_b32 s29, 0xd020
	v_lshlrev_b32_e32 v30, 1, v30
	s_waitcnt vmcnt(0)
	s_branch .LBB0_34

; #define LAS __attribute__((address_space(3)))
; __device__ __forceinline__ void lds_barrier() { asm volatile("s_waitcnt lgkmcnt(0)" ::: "memory"); __builtin_amdgcn_s_barrier(); asm volatile("" ::: "memory"); }
; __device__ __forceinline__ void convert_weight(int wv, const float* __restrict__ src, int ldsrc, int Ksrc, bf16_t* dst, int ldd, int koff, int ntn, const float* kscale, int mode, LAS float* tile, int pidx, int pcnt) {
;     ...
;     for (; t < total; t += G) {
;         LAS float* tl = tile + buf * (128 * 65);
; #pragma unroll
;         for (int i = 0; i < 4; ++i) { const int kk = kk0 + i * 32;
;             tl[kk * 65 + n4 + 0] = v[i][0] * ks[i]; tl[kk * 65 + n4 + 1] = v[i][1] * ks[i]; tl[kk * 65 + n4 + 2] = v[i][2] * ks[i]; tl[kk * 65 + n4 + 3] = v[i][3] * ks[i]; }
;         lds_barrier();
;         const int tn = t % ntn, tk = t / ntn; const int n0 = tn * 64, k0 = tk * 128;
;         if (t + G < total) prefetch(t + G);
.LBB0_34:
	s_mul_i32 s16, s28, 0x8200
	s_add_i32 s34, s16, 0
	v_add3_u32 v11, s34, v26, v38
	s_waitcnt vmcnt(2)
	v_pk_mul_f32 v[36:37], v[2:3], v[28:29] op_sel_hi:[1,0]
	ds_write2_b32 v11, v36, v37 offset1:1
	v_pk_mul_f32 v[36:37], v[4:5], v[28:29] op_sel_hi:[1,0]
	ds_write2_b32 v11, v36, v37 offset0:2 offset1:3
	v_pk_mul_f32 v[36:37], v[6:7], v[32:33] op_sel_hi:[1,0]
	v_add_u32_e32 v13, 0x2080, v11
	ds_write2_b32 v13, v36, v37 offset1:1
	v_pk_mul_f32 v[36:37], v[8:9], v[32:33] op_sel_hi:[1,0]
	v_add_u32_e32 v13, 0x2088, v11
	ds_write2_b32 v13, v36, v37 offset1:1
	v_pk_mul_f32 v[36:37], v[14:15], v[34:35] op_sel_hi:[1,0]
	v_add_u32_e32 v13, 0x4100, v11
	ds_write2_b32 v13, v36, v37 offset1:1
	v_pk_mul_f32 v[36:37], v[16:17], v[34:35] op_sel_hi:[1,0]
	v_add_u32_e32 v13, 0x4108, v11
	ds_write2_b32 v13, v36, v37 offset1:1
	v_pk_mul_f32 v[36:37], v[18:19], v[12:13] op_sel_hi:[1,0]
	v_add_u32_e32 v13, 0x6180, v11
	ds_write2_b32 v13, v36, v37 offset1:1
	v_pk_mul_f32 v[36:37], v[20:21], v[12:13] op_sel_hi:[1,0]
	v_add_u32_e32 v11, 0x6188, v11
	ds_write2_b32 v11, v36, v37 offset1:1
	s_waitcnt lgkmcnt(0)
	s_barrier
	s_add_i32 s31, s26, s48
	s_cmpk_gt_i32 s31, 0xd3f
	s_cselect_b64 s[16:17], -1, 0
	s_cmpk_lt_i32 s31, 0xd40
	s_mov_b64 s[18:19], -1
	s_cbranch_scc1 .LBB0_36
	s_add_i32 s33, s30, s27
	s_mov_b64 s[18:19], 0

; __device__ __forceinline__ int opaque_tid(int wv) { asm volatile("" : "+s"(wv)); unsigned z = 0u; asm volatile("" : "+v"(z)); const int l = __builtin_amdgcn_mbcnt_hi(~0u, __builtin_amdgcn_mbcnt_lo(~0u, z)); return (wv << 6) | l; }
; __device__ __forceinline__ void init_phase(int wv, PP P) {
;     float* hp = (float*)(P->ws + WS_HP); bf16_t* hb = (bf16_t*)((unsigned char*)P->out + DO_HB); float* rsq = (float*)(P->ws + WS_RSQ); float* hsq = (float*)(P->ws + WS_HSQ);
;     const int tid = opaque_tid(wv), w = tid >> 6, lane = tid & 63;
;     for (int row = blockIdx.x * 8 + w; row < MP; row += gridDim.x * 8) {
;         const int b = row / LP, pp = row % LP;
;         const float* src = pp < PADN ? nullptr : (pp < LEADR ? P->meta + (size_t)(pp - PADN) * D : P->x + ((size_t)b * SEQ + (pp - LEADR)) * D);
;         float ss = 0.f;
; #pragma unroll
;         for (int i = 0; i < 8; ++i) {
;             const int c = (i * 64 + lane) * 4; f32x4 v = (f32x4){0.f, 0.f, 0.f, 0.f}; if (src) v = *(const f32x4*)(src + c);
.LBB0_61:
	s_mov_b64 s[10:11], s[0:1]
	s_barrier
	s_load_dwordx4 s[4:7], s[10:11], 0x98
	s_mov_b32 s14, s95
	s_waitcnt vmcnt(2)
	v_mov_b32_e32 v2, 0
	s_waitcnt lgkmcnt(0)
	s_add_u32 s8, s6, 0x27c84000
	v_mbcnt_lo_u32_b32 v2, -1, v2
	v_mbcnt_hi_u32_b32 v2, -1, v2
	v_lshl_or_b32 v39, s14, 6, v2
	s_addc_u32 s9, s7, 0
	v_ashrrev_i32_e32 v3, 6, v39
	s_lshl_b32 s14, s81, 3
	v_add_u32_e32 v36, s14, v3
	v_writelane_b32 v254, s14, 0
	s_movk_i32 s14, 0x4200
	v_mov_b32_e32 v35, 0
	v_cmp_gt_i32_e32 vcc, s14, v36
	s_and_saveexec_b64 s[14:15], vcc
	s_cbranch_execz .LBB0_88
	v_and_b32_e32 v3, 63, v2
	v_lshlrev_b32_e32 v2, 4, v3
	v_lshlrev_b32_e32 v4, 2, v3
	v_lshlrev_b32_e32 v3, 3, v3
	v_xor_b32_e32 v5, 4, v4
	v_xor_b32_e32 v6, 8, v4
	v_xor_b32_e32 v7, 16, v4
	v_xor_b32_e32 v8, 32, v4
	v_xor_b32_e32 v9, 64, v4
	v_xor_b32_e32 v10, 0x80, v4
	v_mov_b32_e32 v4, 0
	s_load_dwordx4 s[32:35], s[0:1], 0x0
	s_lshl_b32 s16, s81, 3
	s_add_u32 s16, s16, s95
	s_waitcnt lgkmcnt(0)
	s_add_u32 s17, s16, 0x0
	s_mul_hi_u32 s18, s17, 0x1f07c2
	s_mul_i32 s19, s18, 0x840
	s_sub_u32 s19, s17, s19
	s_mov_b32 s36, 0
	s_mov_b64 s[20:21], s[32:33]
	s_cmp_lt_u32 s19, 48
	s_cbranch_scc0 .Linit_i0_a
	s_mov_b32 s36, 1
	s_branch .Linit_i0_ld
.Linit_i0_a:
	s_cmp_lt_u32 s19, 64
	s_cbranch_scc0 .Linit_i0_x
	s_sub_u32 s38, s19, 48
	s_lshl_b32 s38, s38, 13
	s_add_u32 s20, s34, s38
	s_addc_u32 s21, s35, 0
	s_branch .Linit_i0_ld
.Linit_i0_x:
	s_lshl_b32 s38, s18, 11
	s_add_u32 s38, s38, s19
	s_sub_u32 s38, s38, 64
	s_lshl_b32 s38, s38, 13
	s_add_u32 s20, s32, s38
	s_addc_u32 s21, s33, 0
.Linit_i0_ld:
	s_add_u32 s22, s20, 0x1000
	s_addc_u32 s23, s21, 0
	global_load_dwordx4 v[40:43], v2, s[20:21]
	global_load_dwordx4 v[44:47], v2, s[20:21] offset:1024
	global_load_dwordx4 v[48:51], v2, s[20:21] offset:2048
	global_load_dwordx4 v[52:55], v2, s[20:21] offset:3072
	global_load_dwordx4 v[56:59], v2, s[22:23]
	global_load_dwordx4 v[60:63], v2, s[22:23] offset:1024
	global_load_dwordx4 v[64:67], v2, s[22:23] offset:2048
	global_load_dwordx4 v[68:71], v2, s[22:23] offset:3072
	s_add_u32 s17, s16, 0x800
	s_mul_hi_u32 s18, s17, 0x1f07c2
	s_mul_i32 s19, s18, 0x840
	s_sub_u32 s19, s17, s19
	s_mov_b32 s37, 0
	s_mov_b64 s[20:21], s[32:33]
	s_cmp_lt_u32 s19, 48
	s_cbranch_scc0 .Linit_i1_a
	s_mov_b32 s37, 1
	s_branch .Linit_i1_ld

; __device__ __forceinline__ float shx(float v, int mask, int lane) { return __int_as_float(__builtin_amdgcn_ds_bpermute((lane ^ mask) << 2, __float_as_int(v))); }
; __device__ __forceinline__ unsigned pack2(float lo, float hi) { unsigned r; asm("v_cvt_pk_bf16_f32 %0, %1, %2" : "=v"(r) : "v"(lo), "v"(hi)); return r; }
; __device__ __forceinline__ void init_phase(int wv, PP P) {
;     ...
;     for (int row = blockIdx.x * 8 + w; row < MP; row += gridDim.x * 8) {
;         const int b = row / LP, pp = row % LP;
;         const float* src = pp < PADN ? nullptr : (pp < LEADR ? P->meta + (size_t)(pp - PADN) * D : P->x + ((size_t)b * SEQ + (pp - LEADR)) * D);
;         float ss = 0.f;
; #pragma unroll
;         for (int i = 0; i < 8; ++i) {
;             const int c = (i * 64 + lane) * 4; f32x4 v = (f32x4){0.f, 0.f, 0.f, 0.f}; if (src) v = *(const f32x4*)(src + c);
;             *(f32x4*)(hp + (size_t)row * D + c) = v; u32x2 o; o.x = pack2(v[0], v[1]); o.y = pack2(v[2], v[3]); *(u32x2*)(hb + (size_t)row * D + c) = o;
;             ss += v[0] * v[0] + v[1] * v[1] + v[2] * v[2] + v[3] * v[3];
;         }
; #pragma unroll
;         for (int o = 1; o < 64; o <<= 1) ss += shx(ss, o, lane);
;         if (lane == 0) rsq[row] = ss;
.Linit_i1_ld:
	s_add_u32 s22, s20, 0x1000
	s_addc_u32 s23, s21, 0
	global_load_dwordx4 v[72:75], v2, s[20:21]
	global_load_dwordx4 v[76:79], v2, s[20:21] offset:1024
	global_load_dwordx4 v[80:83], v2, s[20:21] offset:2048
	global_load_dwordx4 v[84:87], v2, s[20:21] offset:3072
	global_load_dwordx4 v[88:91], v2, s[22:23]
	global_load_dwordx4 v[92:95], v2, s[22:23] offset:1024
	global_load_dwordx4 v[96:99], v2, s[22:23] offset:2048
	global_load_dwordx4 v[100:103], v2, s[22:23] offset:3072
	s_waitcnt vmcnt(8)
	s_cmp_eq_u32 s36, 0
	s_cbranch_scc1 .Linit_p0
	v_mov_b32_e32 v40, 0
	v_mov_b32_e32 v41, 0
	v_mov_b32_e32 v42, 0
	v_mov_b32_e32 v43, 0
	v_mov_b32_e32 v44, 0
	v_mov_b32_e32 v45, 0
	v_mov_b32_e32 v46, 0
	v_mov_b32_e32 v47, 0
	v_mov_b32_e32 v48, 0
	v_mov_b32_e32 v49, 0
	v_mov_b32_e32 v50, 0
	v_mov_b32_e32 v51, 0
	v_mov_b32_e32 v52, 0
	v_mov_b32_e32 v53, 0
	v_mov_b32_e32 v54, 0
	v_mov_b32_e32 v55, 0
	v_mov_b32_e32 v56, 0
	v_mov_b32_e32 v57, 0
	v_mov_b32_e32 v58, 0
	v_mov_b32_e32 v59, 0
	v_mov_b32_e32 v60, 0
	v_mov_b32_e32 v61, 0
	v_mov_b32_e32 v62, 0
	v_mov_b32_e32 v63, 0
	v_mov_b32_e32 v64, 0
	v_mov_b32_e32 v65, 0
	v_mov_b32_e32 v66, 0
	v_mov_b32_e32 v67, 0
	v_mov_b32_e32 v68, 0
	v_mov_b32_e32 v69, 0
	v_mov_b32_e32 v70, 0
	v_mov_b32_e32 v71, 0
.Linit_p0:
	s_add_u32 s17, s16, 0x0
	s_lshl_b32 s38, s17, 13
	s_add_u32 s24, s6, s38
	s_addc_u32 s25, s7, 0
	s_add_u32 s26, s24, 0x1000
	s_addc_u32 s27, s25, 0
	s_lshl_b32 s38, s17, 12
	s_add_u32 s28, s4, s38
	s_addc_u32 s29, s5, 0
	s_lshl_b32 s38, s17, 2
	s_add_u32 s30, s8, s38
	s_addc_u32 s31, s9, 0
	global_store_dwordx4 v2, v[40:43], s[24:25]
	v_cvt_pk_bf16_f32 v14, v40, v41
	v_cvt_pk_bf16_f32 v15, v42, v43
	v_mul_f32_e32 v12, v41, v41
	global_store_dwordx2 v3, v[14:15], s[28:29]
	v_fmac_f32_e32 v12, v40, v40
	v_fmac_f32_e32 v12, v42, v42
	v_fmac_f32_e32 v12, v43, v43
	v_mov_b32_e32 v11, v12
	global_store_dwordx4 v2, v[44:47], s[24:25] offset:1024
	v_cvt_pk_bf16_f32 v16, v44, v45
	v_cvt_pk_bf16_f32 v17, v46, v47
	v_mul_f32_e32 v12, v45, v45
	global_store_dwordx2 v3, v[16:17], s[28:29] offset:512
	v_fmac_f32_e32 v12, v44, v44
	v_fmac_f32_e32 v12, v46, v46
	v_fmac_f32_e32 v12, v47, v47
	v_add_f32_e32 v11, v11, v12
	global_store_dwordx4 v2, v[48:51], s[24:25] offset:2048
	v_cvt_pk_bf16_f32 v14, v48, v49
	v_cvt_pk_bf16_f32 v15, v50, v51
	v_mul_f32_e32 v12, v49, v49
	global_store_dwordx2 v3, v[14:15], s[28:29] offset:1024
	v_fmac_f32_e32 v12, v48, v48
	v_fmac_f32_e32 v12, v50, v50
	v_fmac_f32_e32 v12, v51, v51
	v_add_f32_e32 v11, v11, v12
	global_store_dwordx4 v2, v[52:55], s[24:25] offset:3072
	v_cvt_pk_bf16_f32 v16, v52, v53
	v_cvt_pk_bf16_f32 v17, v54, v55
	v_mul_f32_e32 v12, v53, v53
	global_store_dwordx2 v3, v[16:17], s[28:29] offset:1536
	v_fmac_f32_e32 v12, v52, v52
	v_fmac_f32_e32 v12, v54, v54
	v_fmac_f32_e32 v12, v55, v55
	v_add_f32_e32 v11, v11, v12
	global_store_dwordx4 v2, v[56:59], s[26:27]
	v_cvt_pk_bf16_f32 v14, v56, v57
	v_cvt_pk_bf16_f32 v15, v58, v59
	v_mul_f32_e32 v12, v57, v57
	global_store_dwordx2 v3, v[14:15], s[28:29] offset:2048
	v_fmac_f32_e32 v12, v56, v56
	v_fmac_f32_e32 v12, v58, v58
	v_fmac_f32_e32 v12, v59, v59
	v_add_f32_e32 v11, v11, v12
	global_store_dwordx4 v2, v[60:63], s[26:27] offset:1024
	v_cvt_pk_bf16_f32 v16, v60, v61
	v_cvt_pk_bf16_f32 v17, v62, v63
	v_mul_f32_e32 v12, v61, v61
	global_store_dwordx2 v3, v[16:17], s[28:29] offset:2560
	v_fmac_f32_e32 v12, v60, v60
	v_fmac_f32_e32 v12, v62, v62
	v_fmac_f32_e32 v12, v63, v63
	v_add_f32_e32 v11, v11, v12
	global_store_dwordx4 v2, v[64:67], s[26:27] offset:2048
	v_cvt_pk_bf16_f32 v14, v64, v65
	v_cvt_pk_bf16_f32 v15, v66, v67
	v_mul_f32_e32 v12, v65, v65
	global_store_dwordx2 v3, v[14:15], s[28:29] offset:3072
	v_fmac_f32_e32 v12, v64, v64
	v_fmac_f32_e32 v12, v66, v66
	v_fmac_f32_e32 v12, v67, v67
	v_add_f32_e32 v11, v11, v12
	global_store_dwordx4 v2, v[68:71], s[26:27] offset:3072
	v_cvt_pk_bf16_f32 v16, v68, v69
	v_cvt_pk_bf16_f32 v17, v70, v71
	v_mul_f32_e32 v12, v69, v69
	global_store_dwordx2 v3, v[16:17], s[28:29] offset:3584
	v_fmac_f32_e32 v12, v68, v68
	v_fmac_f32_e32 v12, v70, v70
	v_fmac_f32_e32 v12, v71, v71
	v_add_f32_e32 v11, v11, v12
	ds_bpermute_b32 v13, v5, v11
	s_waitcnt lgkmcnt(0)
	v_add_f32_e32 v11, v11, v13
	ds_bpermute_b32 v13, v6, v11
	s_waitcnt lgkmcnt(0)
	v_add_f32_e32 v11, v11, v13
	ds_bpermute_b32 v13, v7, v11
	s_waitcnt lgkmcnt(0)
	v_add_f32_e32 v11, v11, v13
	ds_bpermute_b32 v13, v8, v11
	s_waitcnt lgkmcnt(0)
	v_add_f32_e32 v11, v11, v13
	ds_bpermute_b32 v13, v9, v11
	s_waitcnt lgkmcnt(0)
	v_add_f32_e32 v11, v11, v13
	ds_bpermute_b32 v13, v10, v11
	s_waitcnt lgkmcnt(0)
	v_add_f32_e32 v11, v11, v13
	s_mov_b64 exec, 1
	global_store_dword v4, v11, s[30:31]
	s_mov_b64 exec, -1
	s_add_u32 s17, s16, 0x1000
	s_mul_hi_u32 s18, s17, 0x1f07c2
	s_mul_i32 s19, s18, 0x840
	s_sub_u32 s19, s17, s19
	s_mov_b32 s36, 0
	s_mov_b64 s[20:21], s[32:33]
	s_cmp_lt_u32 s19, 48
	s_cbranch_scc0 .Linit_i2_a
	s_mov_b32 s36, 1
	s_branch .Linit_i2_ld

; __device__ __forceinline__ float shx(float v, int mask, int lane) { return __int_as_float(__builtin_amdgcn_ds_bpermute((lane ^ mask) << 2, __float_as_int(v))); }
; __device__ __forceinline__ unsigned pack2(float lo, float hi) { unsigned r; asm("v_cvt_pk_bf16_f32 %0, %1, %2" : "=v"(r) : "v"(lo), "v"(hi)); return r; }
; __device__ __forceinline__ void init_phase(int wv, PP P) {
;     ...
;     for (int row = blockIdx.x * 8 + w; row < MP; row += gridDim.x * 8) {
;         const int b = row / LP, pp = row % LP;
;         const float* src = pp < PADN ? nullptr : (pp < LEADR ? P->meta + (size_t)(pp - PADN) * D : P->x + ((size_t)b * SEQ + (pp - LEADR)) * D);
;         float ss = 0.f;
; #pragma unroll
;         for (int i = 0; i < 8; ++i) {
;             const int c = (i * 64 + lane) * 4; f32x4 v = (f32x4){0.f, 0.f, 0.f, 0.f}; if (src) v = *(const f32x4*)(src + c);
;             *(f32x4*)(hp + (size_t)row * D + c) = v; u32x2 o; o.x = pack2(v[0], v[1]); o.y = pack2(v[2], v[3]); *(u32x2*)(hb + (size_t)row * D + c) = o;
;             ss += v[0] * v[0] + v[1] * v[1] + v[2] * v[2] + v[3] * v[3];
;         }
; #pragma unroll
;         for (int o = 1; o < 64; o <<= 1) ss += shx(ss, o, lane);
;         if (lane == 0) rsq[row] = ss;
.Linit_i2_ld:
	s_add_u32 s22, s20, 0x1000
	s_addc_u32 s23, s21, 0
	global_load_dwordx4 v[40:43], v2, s[20:21]
	global_load_dwordx4 v[44:47], v2, s[20:21] offset:1024
	global_load_dwordx4 v[48:51], v2, s[20:21] offset:2048
	global_load_dwordx4 v[52:55], v2, s[20:21] offset:3072
	global_load_dwordx4 v[56:59], v2, s[22:23]
	global_load_dwordx4 v[60:63], v2, s[22:23] offset:1024
	global_load_dwordx4 v[64:67], v2, s[22:23] offset:2048
	global_load_dwordx4 v[68:71], v2, s[22:23] offset:3072
	s_waitcnt vmcnt(25)
	s_cmp_eq_u32 s37, 0
	s_cbranch_scc1 .Linit_p1
	v_mov_b32_e32 v72, 0
	v_mov_b32_e32 v73, 0
	v_mov_b32_e32 v74, 0
	v_mov_b32_e32 v75, 0
	v_mov_b32_e32 v76, 0
	v_mov_b32_e32 v77, 0
	v_mov_b32_e32 v78, 0
	v_mov_b32_e32 v79, 0
	v_mov_b32_e32 v80, 0
	v_mov_b32_e32 v81, 0
	v_mov_b32_e32 v82, 0
	v_mov_b32_e32 v83, 0
	v_mov_b32_e32 v84, 0
	v_mov_b32_e32 v85, 0
	v_mov_b32_e32 v86, 0
	v_mov_b32_e32 v87, 0
	v_mov_b32_e32 v88, 0
	v_mov_b32_e32 v89, 0
	v_mov_b32_e32 v90, 0
	v_mov_b32_e32 v91, 0
	v_mov_b32_e32 v92, 0
	v_mov_b32_e32 v93, 0
	v_mov_b32_e32 v94, 0
	v_mov_b32_e32 v95, 0
	v_mov_b32_e32 v96, 0
	v_mov_b32_e32 v97, 0
	v_mov_b32_e32 v98, 0
	v_mov_b32_e32 v99, 0
	v_mov_b32_e32 v100, 0
	v_mov_b32_e32 v101, 0
	v_mov_b32_e32 v102, 0
	v_mov_b32_e32 v103, 0
.Linit_p1:
	s_add_u32 s17, s16, 0x800
	s_lshl_b32 s38, s17, 13
	s_add_u32 s24, s6, s38
	s_addc_u32 s25, s7, 0
	s_add_u32 s26, s24, 0x1000
	s_addc_u32 s27, s25, 0
	s_lshl_b32 s38, s17, 12
	s_add_u32 s28, s4, s38
	s_addc_u32 s29, s5, 0
	s_lshl_b32 s38, s17, 2
	s_add_u32 s30, s8, s38
	s_addc_u32 s31, s9, 0
	global_store_dwordx4 v2, v[72:75], s[24:25]
	v_cvt_pk_bf16_f32 v14, v72, v73
	v_cvt_pk_bf16_f32 v15, v74, v75
	v_mul_f32_e32 v12, v73, v73
	global_store_dwordx2 v3, v[14:15], s[28:29]
	v_fmac_f32_e32 v12, v72, v72
	v_fmac_f32_e32 v12, v74, v74
	v_fmac_f32_e32 v12, v75, v75
	v_mov_b32_e32 v11, v12
	global_store_dwordx4 v2, v[76:79], s[24:25] offset:1024
	v_cvt_pk_bf16_f32 v16, v76, v77
	v_cvt_pk_bf16_f32 v17, v78, v79
	v_mul_f32_e32 v12, v77, v77
	global_store_dwordx2 v3, v[16:17], s[28:29] offset:512
	v_fmac_f32_e32 v12, v76, v76
	v_fmac_f32_e32 v12, v78, v78
	v_fmac_f32_e32 v12, v79, v79
	v_add_f32_e32 v11, v11, v12
	global_store_dwordx4 v2, v[80:83], s[24:25] offset:2048
	v_cvt_pk_bf16_f32 v14, v80, v81
	v_cvt_pk_bf16_f32 v15, v82, v83
	v_mul_f32_e32 v12, v81, v81
	global_store_dwordx2 v3, v[14:15], s[28:29] offset:1024
	v_fmac_f32_e32 v12, v80, v80
	v_fmac_f32_e32 v12, v82, v82
	v_fmac_f32_e32 v12, v83, v83
	v_add_f32_e32 v11, v11, v12
	global_store_dwordx4 v2, v[84:87], s[24:25] offset:3072
	v_cvt_pk_bf16_f32 v16, v84, v85
	v_cvt_pk_bf16_f32 v17, v86, v87
	v_mul_f32_e32 v12, v85, v85
	global_store_dwordx2 v3, v[16:17], s[28:29] offset:1536
	v_fmac_f32_e32 v12, v84, v84
	v_fmac_f32_e32 v12, v86, v86
	v_fmac_f32_e32 v12, v87, v87
	v_add_f32_e32 v11, v11, v12
	global_store_dwordx4 v2, v[88:91], s[26:27]
	v_cvt_pk_bf16_f32 v14, v88, v89
	v_cvt_pk_bf16_f32 v15, v90, v91
	v_mul_f32_e32 v12, v89, v89
	global_store_dwordx2 v3, v[14:15], s[28:29] offset:2048
	v_fmac_f32_e32 v12, v88, v88
	v_fmac_f32_e32 v12, v90, v90
	v_fmac_f32_e32 v12, v91, v91
	v_add_f32_e32 v11, v11, v12
	global_store_dwordx4 v2, v[92:95], s[26:27] offset:1024
	v_cvt_pk_bf16_f32 v16, v92, v93
	v_cvt_pk_bf16_f32 v17, v94, v95
	v_mul_f32_e32 v12, v93, v93
	global_store_dwordx2 v3, v[16:17], s[28:29] offset:2560
	v_fmac_f32_e32 v12, v92, v92
	v_fmac_f32_e32 v12, v94, v94
	v_fmac_f32_e32 v12, v95, v95
	v_add_f32_e32 v11, v11, v12
	global_store_dwordx4 v2, v[96:99], s[26:27] offset:2048
	v_cvt_pk_bf16_f32 v14, v96, v97
	v_cvt_pk_bf16_f32 v15, v98, v99
	v_mul_f32_e32 v12, v97, v97
	global_store_dwordx2 v3, v[14:15], s[28:29] offset:3072
	v_fmac_f32_e32 v12, v96, v96
	v_fmac_f32_e32 v12, v98, v98
	v_fmac_f32_e32 v12, v99, v99
	v_add_f32_e32 v11, v11, v12
	global_store_dwordx4 v2, v[100:103], s[26:27] offset:3072
	v_cvt_pk_bf16_f32 v16, v100, v101
	v_cvt_pk_bf16_f32 v17, v102, v103
	v_mul_f32_e32 v12, v101, v101
	global_store_dwordx2 v3, v[16:17], s[28:29] offset:3584
	v_fmac_f32_e32 v12, v100, v100
	v_fmac_f32_e32 v12, v102, v102
	v_fmac_f32_e32 v12, v103, v103
	v_add_f32_e32 v11, v11, v12
	ds_bpermute_b32 v13, v5, v11
	s_waitcnt lgkmcnt(0)
	v_add_f32_e32 v11, v11, v13
	ds_bpermute_b32 v13, v6, v11
	s_waitcnt lgkmcnt(0)
	v_add_f32_e32 v11, v11, v13
	ds_bpermute_b32 v13, v7, v11
	s_waitcnt lgkmcnt(0)
	v_add_f32_e32 v11, v11, v13
	ds_bpermute_b32 v13, v8, v11
	s_waitcnt lgkmcnt(0)
	v_add_f32_e32 v11, v11, v13
	ds_bpermute_b32 v13, v9, v11
	s_waitcnt lgkmcnt(0)
	v_add_f32_e32 v11, v11, v13
	ds_bpermute_b32 v13, v10, v11
	s_waitcnt lgkmcnt(0)
	v_add_f32_e32 v11, v11, v13
	s_mov_b64 exec, 1
	global_store_dword v4, v11, s[30:31]
	s_mov_b64 exec, -1
	s_add_u32 s17, s16, 0x1800
	s_mul_hi_u32 s18, s17, 0x1f07c2
	s_mul_i32 s19, s18, 0x840
	s_sub_u32 s19, s17, s19
	s_mov_b32 s37, 0
	s_mov_b64 s[20:21], s[32:33]
	s_cmp_lt_u32 s19, 48
	s_cbranch_scc0 .Linit_i3_a
	s_mov_b32 s37, 1
	s_branch .Linit_i3_ld

; __device__ __forceinline__ float shx(float v, int mask, int lane) { return __int_as_float(__builtin_amdgcn_ds_bpermute((lane ^ mask) << 2, __float_as_int(v))); }
; __device__ __forceinline__ unsigned pack2(float lo, float hi) { unsigned r; asm("v_cvt_pk_bf16_f32 %0, %1, %2" : "=v"(r) : "v"(lo), "v"(hi)); return r; }
; __device__ __forceinline__ void init_phase(int wv, PP P) {
;     ...
;     for (int row = blockIdx.x * 8 + w; row < MP; row += gridDim.x * 8) {
;         const int b = row / LP, pp = row % LP;
;         const float* src = pp < PADN ? nullptr : (pp < LEADR ? P->meta + (size_t)(pp - PADN) * D : P->x + ((size_t)b * SEQ + (pp - LEADR)) * D);
;         float ss = 0.f;
; #pragma unroll
;         for (int i = 0; i < 8; ++i) {
;             const int c = (i * 64 + lane) * 4; f32x4 v = (f32x4){0.f, 0.f, 0.f, 0.f}; if (src) v = *(const f32x4*)(src + c);
;             *(f32x4*)(hp + (size_t)row * D + c) = v; u32x2 o; o.x = pack2(v[0], v[1]); o.y = pack2(v[2], v[3]); *(u32x2*)(hb + (size_t)row * D + c) = o;
;             ss += v[0] * v[0] + v[1] * v[1] + v[2] * v[2] + v[3] * v[3];
;         }
; #pragma unroll
;         for (int o = 1; o < 64; o <<= 1) ss += shx(ss, o, lane);
;         if (lane == 0) rsq[row] = ss;
.Linit_i3_ld:
	s_add_u32 s22, s20, 0x1000
	s_addc_u32 s23, s21, 0
	global_load_dwordx4 v[72:75], v2, s[20:21]
	global_load_dwordx4 v[76:79], v2, s[20:21] offset:1024
	global_load_dwordx4 v[80:83], v2, s[20:21] offset:2048
	global_load_dwordx4 v[84:87], v2, s[20:21] offset:3072
	global_load_dwordx4 v[88:91], v2, s[22:23]
	global_load_dwordx4 v[92:95], v2, s[22:23] offset:1024
	global_load_dwordx4 v[96:99], v2, s[22:23] offset:2048
	global_load_dwordx4 v[100:103], v2, s[22:23] offset:3072
	s_waitcnt vmcnt(25)
	s_cmp_eq_u32 s36, 0
	s_cbranch_scc1 .Linit_p2
	v_mov_b32_e32 v40, 0
	v_mov_b32_e32 v41, 0
	v_mov_b32_e32 v42, 0
	v_mov_b32_e32 v43, 0
	v_mov_b32_e32 v44, 0
	v_mov_b32_e32 v45, 0
	v_mov_b32_e32 v46, 0
	v_mov_b32_e32 v47, 0
	v_mov_b32_e32 v48, 0
	v_mov_b32_e32 v49, 0
	v_mov_b32_e32 v50, 0
	v_mov_b32_e32 v51, 0
	v_mov_b32_e32 v52, 0
	v_mov_b32_e32 v53, 0
	v_mov_b32_e32 v54, 0
	v_mov_b32_e32 v55, 0
	v_mov_b32_e32 v56, 0
	v_mov_b32_e32 v57, 0
	v_mov_b32_e32 v58, 0
	v_mov_b32_e32 v59, 0
	v_mov_b32_e32 v60, 0
	v_mov_b32_e32 v61, 0
	v_mov_b32_e32 v62, 0
	v_mov_b32_e32 v63, 0
	v_mov_b32_e32 v64, 0
	v_mov_b32_e32 v65, 0
	v_mov_b32_e32 v66, 0
	v_mov_b32_e32 v67, 0
	v_mov_b32_e32 v68, 0
	v_mov_b32_e32 v69, 0
	v_mov_b32_e32 v70, 0
	v_mov_b32_e32 v71, 0
.Linit_p2:
	s_add_u32 s17, s16, 0x1000
	s_lshl_b32 s38, s17, 13
	s_add_u32 s24, s6, s38
	s_addc_u32 s25, s7, 0
	s_add_u32 s26, s24, 0x1000
	s_addc_u32 s27, s25, 0
	s_lshl_b32 s38, s17, 12
	s_add_u32 s28, s4, s38
	s_addc_u32 s29, s5, 0
	s_lshl_b32 s38, s17, 2
	s_add_u32 s30, s8, s38
	s_addc_u32 s31, s9, 0
	global_store_dwordx4 v2, v[40:43], s[24:25]
	v_cvt_pk_bf16_f32 v14, v40, v41
	v_cvt_pk_bf16_f32 v15, v42, v43
	v_mul_f32_e32 v12, v41, v41
	global_store_dwordx2 v3, v[14:15], s[28:29]
	v_fmac_f32_e32 v12, v40, v40
	v_fmac_f32_e32 v12, v42, v42
	v_fmac_f32_e32 v12, v43, v43
	v_mov_b32_e32 v11, v12
	global_store_dwordx4 v2, v[44:47], s[24:25] offset:1024
	v_cvt_pk_bf16_f32 v16, v44, v45
	v_cvt_pk_bf16_f32 v17, v46, v47
	v_mul_f32_e32 v12, v45, v45
	global_store_dwordx2 v3, v[16:17], s[28:29] offset:512
	v_fmac_f32_e32 v12, v44, v44
	v_fmac_f32_e32 v12, v46, v46
	v_fmac_f32_e32 v12, v47, v47
	v_add_f32_e32 v11, v11, v12
	global_store_dwordx4 v2, v[48:51], s[24:25] offset:2048
	v_cvt_pk_bf16_f32 v14, v48, v49
	v_cvt_pk_bf16_f32 v15, v50, v51
	v_mul_f32_e32 v12, v49, v49
	global_store_dwordx2 v3, v[14:15], s[28:29] offset:1024
	v_fmac_f32_e32 v12, v48, v48
	v_fmac_f32_e32 v12, v50, v50
	v_fmac_f32_e32 v12, v51, v51
	v_add_f32_e32 v11, v11, v12
	global_store_dwordx4 v2, v[52:55], s[24:25] offset:3072
	v_cvt_pk_bf16_f32 v16, v52, v53
	v_cvt_pk_bf16_f32 v17, v54, v55
	v_mul_f32_e32 v12, v53, v53
	global_store_dwordx2 v3, v[16:17], s[28:29] offset:1536
	v_fmac_f32_e32 v12, v52, v52
	v_fmac_f32_e32 v12, v54, v54
	v_fmac_f32_e32 v12, v55, v55
	v_add_f32_e32 v11, v11, v12
	global_store_dwordx4 v2, v[56:59], s[26:27]
	v_cvt_pk_bf16_f32 v14, v56, v57
	v_cvt_pk_bf16_f32 v15, v58, v59
	v_mul_f32_e32 v12, v57, v57
	global_store_dwordx2 v3, v[14:15], s[28:29] offset:2048
	v_fmac_f32_e32 v12, v56, v56
	v_fmac_f32_e32 v12, v58, v58
	v_fmac_f32_e32 v12, v59, v59
	v_add_f32_e32 v11, v11, v12
	global_store_dwordx4 v2, v[60:63], s[26:27] offset:1024
	v_cvt_pk_bf16_f32 v16, v60, v61
	v_cvt_pk_bf16_f32 v17, v62, v63
	v_mul_f32_e32 v12, v61, v61
	global_store_dwordx2 v3, v[16:17], s[28:29] offset:2560
	v_fmac_f32_e32 v12, v60, v60
	v_fmac_f32_e32 v12, v62, v62
	v_fmac_f32_e32 v12, v63, v63
	v_add_f32_e32 v11, v11, v12
	global_store_dwordx4 v2, v[64:67], s[26:27] offset:2048
	v_cvt_pk_bf16_f32 v14, v64, v65
	v_cvt_pk_bf16_f32 v15, v66, v67
	v_mul_f32_e32 v12, v65, v65
	global_store_dwordx2 v3, v[14:15], s[28:29] offset:3072
	v_fmac_f32_e32 v12, v64, v64
	v_fmac_f32_e32 v12, v66, v66
	v_fmac_f32_e32 v12, v67, v67
	v_add_f32_e32 v11, v11, v12
	global_store_dwordx4 v2, v[68:71], s[26:27] offset:3072
	v_cvt_pk_bf16_f32 v16, v68, v69
	v_cvt_pk_bf16_f32 v17, v70, v71
	v_mul_f32_e32 v12, v69, v69
	global_store_dwordx2 v3, v[16:17], s[28:29] offset:3584
	v_fmac_f32_e32 v12, v68, v68
	v_fmac_f32_e32 v12, v70, v70
	v_fmac_f32_e32 v12, v71, v71
	v_add_f32_e32 v11, v11, v12
	ds_bpermute_b32 v13, v5, v11
	s_waitcnt lgkmcnt(0)
	v_add_f32_e32 v11, v11, v13
	ds_bpermute_b32 v13, v6, v11
	s_waitcnt lgkmcnt(0)
	v_add_f32_e32 v11, v11, v13
	ds_bpermute_b32 v13, v7, v11
	s_waitcnt lgkmcnt(0)
	v_add_f32_e32 v11, v11, v13
	ds_bpermute_b32 v13, v8, v11
	s_waitcnt lgkmcnt(0)
	v_add_f32_e32 v11, v11, v13
	ds_bpermute_b32 v13, v9, v11
	s_waitcnt lgkmcnt(0)
	v_add_f32_e32 v11, v11, v13
	ds_bpermute_b32 v13, v10, v11
	s_waitcnt lgkmcnt(0)
	v_add_f32_e32 v11, v11, v13
	s_mov_b64 exec, 1
	global_store_dword v4, v11, s[30:31]
	s_mov_b64 exec, -1
	s_add_u32 s17, s16, 0x2000
	s_mul_hi_u32 s18, s17, 0x1f07c2
	s_mul_i32 s19, s18, 0x840
	s_sub_u32 s19, s17, s19
	s_mov_b32 s36, 0
	s_mov_b64 s[20:21], s[32:33]
	s_cmp_lt_u32 s19, 48
	s_cbranch_scc0 .Linit_i4_a
	s_mov_b32 s36, 1
	s_branch .Linit_i4_ld

; __device__ __forceinline__ float shx(float v, int mask, int lane) { return __int_as_float(__builtin_amdgcn_ds_bpermute((lane ^ mask) << 2, __float_as_int(v))); }
; __device__ __forceinline__ unsigned pack2(float lo, float hi) { unsigned r; asm("v_cvt_pk_bf16_f32 %0, %1, %2" : "=v"(r) : "v"(lo), "v"(hi)); return r; }
; __device__ __forceinline__ void init_phase(int wv, PP P) {
;     ...
;     for (int row = blockIdx.x * 8 + w; row < MP; row += gridDim.x * 8) {
;         const int b = row / LP, pp = row % LP;
;         const float* src = pp < PADN ? nullptr : (pp < LEADR ? P->meta + (size_t)(pp - PADN) * D : P->x + ((size_t)b * SEQ + (pp - LEADR)) * D);
;         float ss = 0.f;
; #pragma unroll
;         for (int i = 0; i < 8; ++i) {
;             const int c = (i * 64 + lane) * 4; f32x4 v = (f32x4){0.f, 0.f, 0.f, 0.f}; if (src) v = *(const f32x4*)(src + c);
;             *(f32x4*)(hp + (size_t)row * D + c) = v; u32x2 o; o.x = pack2(v[0], v[1]); o.y = pack2(v[2], v[3]); *(u32x2*)(hb + (size_t)row * D + c) = o;
;             ss += v[0] * v[0] + v[1] * v[1] + v[2] * v[2] + v[3] * v[3];
;         }
; #pragma unroll
;         for (int o = 1; o < 64; o <<= 1) ss += shx(ss, o, lane);
;         if (lane == 0) rsq[row] = ss;
.Linit_p3:
	s_add_u32 s17, s16, 0x1800
	s_lshl_b32 s38, s17, 13
	s_add_u32 s24, s6, s38
	s_addc_u32 s25, s7, 0
	s_add_u32 s26, s24, 0x1000
	s_addc_u32 s27, s25, 0
	s_lshl_b32 s38, s17, 12
	s_add_u32 s28, s4, s38
	s_addc_u32 s29, s5, 0
	s_lshl_b32 s38, s17, 2
	s_add_u32 s30, s8, s38
	s_addc_u32 s31, s9, 0
	global_store_dwordx4 v2, v[72:75], s[24:25]
	v_cvt_pk_bf16_f32 v14, v72, v73
	v_cvt_pk_bf16_f32 v15, v74, v75
	v_mul_f32_e32 v12, v73, v73
	global_store_dwordx2 v3, v[14:15], s[28:29]
	v_fmac_f32_e32 v12, v72, v72
	v_fmac_f32_e32 v12, v74, v74
	v_fmac_f32_e32 v12, v75, v75
	v_mov_b32_e32 v11, v12
	global_store_dwordx4 v2, v[76:79], s[24:25] offset:1024
	v_cvt_pk_bf16_f32 v16, v76, v77
	v_cvt_pk_bf16_f32 v17, v78, v79
	v_mul_f32_e32 v12, v77, v77
	global_store_dwordx2 v3, v[16:17], s[28:29] offset:512
	v_fmac_f32_e32 v12, v76, v76
	v_fmac_f32_e32 v12, v78, v78
	v_fmac_f32_e32 v12, v79, v79
	v_add_f32_e32 v11, v11, v12
	global_store_dwordx4 v2, v[80:83], s[24:25] offset:2048
	v_cvt_pk_bf16_f32 v14, v80, v81
	v_cvt_pk_bf16_f32 v15, v82, v83
	v_mul_f32_e32 v12, v81, v81
	global_store_dwordx2 v3, v[14:15], s[28:29] offset:1024
	v_fmac_f32_e32 v12, v80, v80
	v_fmac_f32_e32 v12, v82, v82
	v_fmac_f32_e32 v12, v83, v83
	v_add_f32_e32 v11, v11, v12
	global_store_dwordx4 v2, v[84:87], s[24:25] offset:3072
	v_cvt_pk_bf16_f32 v16, v84, v85
	v_cvt_pk_bf16_f32 v17, v86, v87
	v_mul_f32_e32 v12, v85, v85
	global_store_dwordx2 v3, v[16:17], s[28:29] offset:1536
	v_fmac_f32_e32 v12, v84, v84
	v_fmac_f32_e32 v12, v86, v86
	v_fmac_f32_e32 v12, v87, v87
	v_add_f32_e32 v11, v11, v12
	global_store_dwordx4 v2, v[88:91], s[26:27]
	v_cvt_pk_bf16_f32 v14, v88, v89
	v_cvt_pk_bf16_f32 v15, v90, v91
	v_mul_f32_e32 v12, v89, v89
	global_store_dwordx2 v3, v[14:15], s[28:29] offset:2048
	v_fmac_f32_e32 v12, v88, v88
	v_fmac_f32_e32 v12, v90, v90
	v_fmac_f32_e32 v12, v91, v91
	v_add_f32_e32 v11, v11, v12
	global_store_dwordx4 v2, v[92:95], s[26:27] offset:1024
	v_cvt_pk_bf16_f32 v16, v92, v93
	v_cvt_pk_bf16_f32 v17, v94, v95
	v_mul_f32_e32 v12, v93, v93
	global_store_dwordx2 v3, v[16:17], s[28:29] offset:2560
	v_fmac_f32_e32 v12, v92, v92
	v_fmac_f32_e32 v12, v94, v94
	v_fmac_f32_e32 v12, v95, v95
	v_add_f32_e32 v11, v11, v12
	global_store_dwordx4 v2, v[96:99], s[26:27] offset:2048
	v_cvt_pk_bf16_f32 v14, v96, v97
	v_cvt_pk_bf16_f32 v15, v98, v99
	v_mul_f32_e32 v12, v97, v97
	global_store_dwordx2 v3, v[14:15], s[28:29] offset:3072
	v_fmac_f32_e32 v12, v96, v96
	v_fmac_f32_e32 v12, v98, v98
	v_fmac_f32_e32 v12, v99, v99
	v_add_f32_e32 v11, v11, v12
	global_store_dwordx4 v2, v[100:103], s[26:27] offset:3072
	v_cvt_pk_bf16_f32 v16, v100, v101
	v_cvt_pk_bf16_f32 v17, v102, v103
	v_mul_f32_e32 v12, v101, v101
	global_store_dwordx2 v3, v[16:17], s[28:29] offset:3584
	v_fmac_f32_e32 v12, v100, v100
	v_fmac_f32_e32 v12, v102, v102
	v_fmac_f32_e32 v12, v103, v103
	v_add_f32_e32 v11, v11, v12
	ds_bpermute_b32 v13, v5, v11
	s_waitcnt lgkmcnt(0)
	v_add_f32_e32 v11, v11, v13
	ds_bpermute_b32 v13, v6, v11
	s_waitcnt lgkmcnt(0)
	v_add_f32_e32 v11, v11, v13
	ds_bpermute_b32 v13, v7, v11
	s_waitcnt lgkmcnt(0)
	v_add_f32_e32 v11, v11, v13
	ds_bpermute_b32 v13, v8, v11
	s_waitcnt lgkmcnt(0)
	v_add_f32_e32 v11, v11, v13
	ds_bpermute_b32 v13, v9, v11
	s_waitcnt lgkmcnt(0)
	v_add_f32_e32 v11, v11, v13
	ds_bpermute_b32 v13, v10, v11
	s_waitcnt lgkmcnt(0)
	v_add_f32_e32 v11, v11, v13
	s_mov_b64 exec, 1
	global_store_dword v4, v11, s[30:31]
	s_mov_b64 exec, -1
	s_add_u32 s17, s16, 0x2800
	s_mul_hi_u32 s18, s17, 0x1f07c2
	s_mul_i32 s19, s18, 0x840
	s_sub_u32 s19, s17, s19
	s_mov_b32 s37, 0
	s_mov_b64 s[20:21], s[32:33]
	s_cmp_lt_u32 s19, 48
	s_cbranch_scc0 .Linit_i5_a
	s_mov_b32 s37, 1
	s_branch .Linit_i5_ld

; __device__ __forceinline__ float shx(float v, int mask, int lane) { return __int_as_float(__builtin_amdgcn_ds_bpermute((lane ^ mask) << 2, __float_as_int(v))); }
; __device__ __forceinline__ unsigned pack2(float lo, float hi) { unsigned r; asm("v_cvt_pk_bf16_f32 %0, %1, %2" : "=v"(r) : "v"(lo), "v"(hi)); return r; }
; __device__ __forceinline__ void init_phase(int wv, PP P) {
;     ...
;     for (int row = blockIdx.x * 8 + w; row < MP; row += gridDim.x * 8) {
;         const int b = row / LP, pp = row % LP;
;         const float* src = pp < PADN ? nullptr : (pp < LEADR ? P->meta + (size_t)(pp - PADN) * D : P->x + ((size_t)b * SEQ + (pp - LEADR)) * D);
;         float ss = 0.f;
; #pragma unroll
;         for (int i = 0; i < 8; ++i) {
;             const int c = (i * 64 + lane) * 4; f32x4 v = (f32x4){0.f, 0.f, 0.f, 0.f}; if (src) v = *(const f32x4*)(src + c);
;             *(f32x4*)(hp + (size_t)row * D + c) = v; u32x2 o; o.x = pack2(v[0], v[1]); o.y = pack2(v[2], v[3]); *(u32x2*)(hb + (size_t)row * D + c) = o;
;             ss += v[0] * v[0] + v[1] * v[1] + v[2] * v[2] + v[3] * v[3];
;         }
; #pragma unroll
;         for (int o = 1; o < 64; o <<= 1) ss += shx(ss, o, lane);
;         if (lane == 0) rsq[row] = ss;
.Linit_p4:
	s_add_u32 s17, s16, 0x2000
	s_lshl_b32 s38, s17, 13
	s_add_u32 s24, s6, s38
	s_addc_u32 s25, s7, 0
	s_add_u32 s26, s24, 0x1000
	s_addc_u32 s27, s25, 0
	s_lshl_b32 s38, s17, 12
	s_add_u32 s28, s4, s38
	s_addc_u32 s29, s5, 0
	s_lshl_b32 s38, s17, 2
	s_add_u32 s30, s8, s38
	s_addc_u32 s31, s9, 0
	global_store_dwordx4 v2, v[40:43], s[24:25]
	v_cvt_pk_bf16_f32 v14, v40, v41
	v_cvt_pk_bf16_f32 v15, v42, v43
	v_mul_f32_e32 v12, v41, v41
	global_store_dwordx2 v3, v[14:15], s[28:29]
	v_fmac_f32_e32 v12, v40, v40
	v_fmac_f32_e32 v12, v42, v42
	v_fmac_f32_e32 v12, v43, v43
	v_mov_b32_e32 v11, v12
	global_store_dwordx4 v2, v[44:47], s[24:25] offset:1024
	v_cvt_pk_bf16_f32 v16, v44, v45
	v_cvt_pk_bf16_f32 v17, v46, v47
	v_mul_f32_e32 v12, v45, v45
	global_store_dwordx2 v3, v[16:17], s[28:29] offset:512
	v_fmac_f32_e32 v12, v44, v44
	v_fmac_f32_e32 v12, v46, v46
	v_fmac_f32_e32 v12, v47, v47
	v_add_f32_e32 v11, v11, v12
	global_store_dwordx4 v2, v[48:51], s[24:25] offset:2048
	v_cvt_pk_bf16_f32 v14, v48, v49
	v_cvt_pk_bf16_f32 v15, v50, v51
	v_mul_f32_e32 v12, v49, v49
	global_store_dwordx2 v3, v[14:15], s[28:29] offset:1024
	v_fmac_f32_e32 v12, v48, v48
	v_fmac_f32_e32 v12, v50, v50
	v_fmac_f32_e32 v12, v51, v51
	v_add_f32_e32 v11, v11, v12
	global_store_dwordx4 v2, v[52:55], s[24:25] offset:3072
	v_cvt_pk_bf16_f32 v16, v52, v53
	v_cvt_pk_bf16_f32 v17, v54, v55
	v_mul_f32_e32 v12, v53, v53
	global_store_dwordx2 v3, v[16:17], s[28:29] offset:1536
	v_fmac_f32_e32 v12, v52, v52
	v_fmac_f32_e32 v12, v54, v54
	v_fmac_f32_e32 v12, v55, v55
	v_add_f32_e32 v11, v11, v12
	global_store_dwordx4 v2, v[56:59], s[26:27]
	v_cvt_pk_bf16_f32 v14, v56, v57
	v_cvt_pk_bf16_f32 v15, v58, v59
	v_mul_f32_e32 v12, v57, v57
	global_store_dwordx2 v3, v[14:15], s[28:29] offset:2048
	v_fmac_f32_e32 v12, v56, v56
	v_fmac_f32_e32 v12, v58, v58
	v_fmac_f32_e32 v12, v59, v59
	v_add_f32_e32 v11, v11, v12
	global_store_dwordx4 v2, v[60:63], s[26:27] offset:1024
	v_cvt_pk_bf16_f32 v16, v60, v61
	v_cvt_pk_bf16_f32 v17, v62, v63
	v_mul_f32_e32 v12, v61, v61
	global_store_dwordx2 v3, v[16:17], s[28:29] offset:2560
	v_fmac_f32_e32 v12, v60, v60
	v_fmac_f32_e32 v12, v62, v62
	v_fmac_f32_e32 v12, v63, v63
	v_add_f32_e32 v11, v11, v12
	global_store_dwordx4 v2, v[64:67], s[26:27] offset:2048
	v_cvt_pk_bf16_f32 v14, v64, v65
	v_cvt_pk_bf16_f32 v15, v66, v67
	v_mul_f32_e32 v12, v65, v65
	global_store_dwordx2 v3, v[14:15], s[28:29] offset:3072
	v_fmac_f32_e32 v12, v64, v64
	v_fmac_f32_e32 v12, v66, v66
	v_fmac_f32_e32 v12, v67, v67
	v_add_f32_e32 v11, v11, v12
	global_store_dwordx4 v2, v[68:71], s[26:27] offset:3072
	v_cvt_pk_bf16_f32 v16, v68, v69
	v_cvt_pk_bf16_f32 v17, v70, v71
	v_mul_f32_e32 v12, v69, v69
	global_store_dwordx2 v3, v[16:17], s[28:29] offset:3584
	v_fmac_f32_e32 v12, v68, v68
	v_fmac_f32_e32 v12, v70, v70
	v_fmac_f32_e32 v12, v71, v71
	v_add_f32_e32 v11, v11, v12
	ds_bpermute_b32 v13, v5, v11
	s_waitcnt lgkmcnt(0)
	v_add_f32_e32 v11, v11, v13
	ds_bpermute_b32 v13, v6, v11
	s_waitcnt lgkmcnt(0)
	v_add_f32_e32 v11, v11, v13
	ds_bpermute_b32 v13, v7, v11
	s_waitcnt lgkmcnt(0)
	v_add_f32_e32 v11, v11, v13
	ds_bpermute_b32 v13, v8, v11
	s_waitcnt lgkmcnt(0)
	v_add_f32_e32 v11, v11, v13
	ds_bpermute_b32 v13, v9, v11
	s_waitcnt lgkmcnt(0)
	v_add_f32_e32 v11, v11, v13
	ds_bpermute_b32 v13, v10, v11
	s_waitcnt lgkmcnt(0)
	v_add_f32_e32 v11, v11, v13
	s_mov_b64 exec, 1
	global_store_dword v4, v11, s[30:31]
	s_mov_b64 exec, -1
	s_add_u32 s17, s16, 0x3000
	s_mul_hi_u32 s18, s17, 0x1f07c2
	s_mul_i32 s19, s18, 0x840
	s_sub_u32 s19, s17, s19
	s_mov_b32 s36, 0
	s_mov_b64 s[20:21], s[32:33]
	s_cmp_lt_u32 s19, 48
	s_cbranch_scc0 .Linit_i6_a
	s_mov_b32 s36, 1
	s_branch .Linit_i6_ld

; __device__ __forceinline__ float shx(float v, int mask, int lane) { return __int_as_float(__builtin_amdgcn_ds_bpermute((lane ^ mask) << 2, __float_as_int(v))); }
; __device__ __forceinline__ unsigned pack2(float lo, float hi) { unsigned r; asm("v_cvt_pk_bf16_f32 %0, %1, %2" : "=v"(r) : "v"(lo), "v"(hi)); return r; }
; __device__ __forceinline__ void init_phase(int wv, PP P) {
;     ...
;     for (int row = blockIdx.x * 8 + w; row < MP; row += gridDim.x * 8) {
;         const int b = row / LP, pp = row % LP;
;         const float* src = pp < PADN ? nullptr : (pp < LEADR ? P->meta + (size_t)(pp - PADN) * D : P->x + ((size_t)b * SEQ + (pp - LEADR)) * D);
;         float ss = 0.f;
; #pragma unroll
;         for (int i = 0; i < 8; ++i) {
;             const int c = (i * 64 + lane) * 4; f32x4 v = (f32x4){0.f, 0.f, 0.f, 0.f}; if (src) v = *(const f32x4*)(src + c);
;             *(f32x4*)(hp + (size_t)row * D + c) = v; u32x2 o; o.x = pack2(v[0], v[1]); o.y = pack2(v[2], v[3]); *(u32x2*)(hb + (size_t)row * D + c) = o;
;             ss += v[0] * v[0] + v[1] * v[1] + v[2] * v[2] + v[3] * v[3];
;         }
; #pragma unroll
;         for (int o = 1; o < 64; o <<= 1) ss += shx(ss, o, lane);
;         if (lane == 0) rsq[row] = ss;
.Linit_p5:
	s_add_u32 s17, s16, 0x2800
	s_lshl_b32 s38, s17, 13
	s_add_u32 s24, s6, s38
	s_addc_u32 s25, s7, 0
	s_add_u32 s26, s24, 0x1000
	s_addc_u32 s27, s25, 0
	s_lshl_b32 s38, s17, 12
	s_add_u32 s28, s4, s38
	s_addc_u32 s29, s5, 0
	s_lshl_b32 s38, s17, 2
	s_add_u32 s30, s8, s38
	s_addc_u32 s31, s9, 0
	global_store_dwordx4 v2, v[72:75], s[24:25]
	v_cvt_pk_bf16_f32 v14, v72, v73
	v_cvt_pk_bf16_f32 v15, v74, v75
	v_mul_f32_e32 v12, v73, v73
	global_store_dwordx2 v3, v[14:15], s[28:29]
	v_fmac_f32_e32 v12, v72, v72
	v_fmac_f32_e32 v12, v74, v74
	v_fmac_f32_e32 v12, v75, v75
	v_mov_b32_e32 v11, v12
	global_store_dwordx4 v2, v[76:79], s[24:25] offset:1024
	v_cvt_pk_bf16_f32 v16, v76, v77
	v_cvt_pk_bf16_f32 v17, v78, v79
	v_mul_f32_e32 v12, v77, v77
	global_store_dwordx2 v3, v[16:17], s[28:29] offset:512
	v_fmac_f32_e32 v12, v76, v76
	v_fmac_f32_e32 v12, v78, v78
	v_fmac_f32_e32 v12, v79, v79
	v_add_f32_e32 v11, v11, v12
	global_store_dwordx4 v2, v[80:83], s[24:25] offset:2048
	v_cvt_pk_bf16_f32 v14, v80, v81
	v_cvt_pk_bf16_f32 v15, v82, v83
	v_mul_f32_e32 v12, v81, v81
	global_store_dwordx2 v3, v[14:15], s[28:29] offset:1024
	v_fmac_f32_e32 v12, v80, v80
	v_fmac_f32_e32 v12, v82, v82
	v_fmac_f32_e32 v12, v83, v83
	v_add_f32_e32 v11, v11, v12
	global_store_dwordx4 v2, v[84:87], s[24:25] offset:3072
	v_cvt_pk_bf16_f32 v16, v84, v85
	v_cvt_pk_bf16_f32 v17, v86, v87
	v_mul_f32_e32 v12, v85, v85
	global_store_dwordx2 v3, v[16:17], s[28:29] offset:1536
	v_fmac_f32_e32 v12, v84, v84
	v_fmac_f32_e32 v12, v86, v86
	v_fmac_f32_e32 v12, v87, v87
	v_add_f32_e32 v11, v11, v12
	global_store_dwordx4 v2, v[88:91], s[26:27]
	v_cvt_pk_bf16_f32 v14, v88, v89
	v_cvt_pk_bf16_f32 v15, v90, v91
	v_mul_f32_e32 v12, v89, v89
	global_store_dwordx2 v3, v[14:15], s[28:29] offset:2048
	v_fmac_f32_e32 v12, v88, v88
	v_fmac_f32_e32 v12, v90, v90
	v_fmac_f32_e32 v12, v91, v91
	v_add_f32_e32 v11, v11, v12
	global_store_dwordx4 v2, v[92:95], s[26:27] offset:1024
	v_cvt_pk_bf16_f32 v16, v92, v93
	v_cvt_pk_bf16_f32 v17, v94, v95
	v_mul_f32_e32 v12, v93, v93
	global_store_dwordx2 v3, v[16:17], s[28:29] offset:2560
	v_fmac_f32_e32 v12, v92, v92
	v_fmac_f32_e32 v12, v94, v94
	v_fmac_f32_e32 v12, v95, v95
	v_add_f32_e32 v11, v11, v12
	global_store_dwordx4 v2, v[96:99], s[26:27] offset:2048
	v_cvt_pk_bf16_f32 v14, v96, v97
	v_cvt_pk_bf16_f32 v15, v98, v99
	v_mul_f32_e32 v12, v97, v97
	global_store_dwordx2 v3, v[14:15], s[28:29] offset:3072
	v_fmac_f32_e32 v12, v96, v96
	v_fmac_f32_e32 v12, v98, v98
	v_fmac_f32_e32 v12, v99, v99
	v_add_f32_e32 v11, v11, v12
	global_store_dwordx4 v2, v[100:103], s[26:27] offset:3072
	v_cvt_pk_bf16_f32 v16, v100, v101
	v_cvt_pk_bf16_f32 v17, v102, v103
	v_mul_f32_e32 v12, v101, v101
	global_store_dwordx2 v3, v[16:17], s[28:29] offset:3584
	v_fmac_f32_e32 v12, v100, v100
	v_fmac_f32_e32 v12, v102, v102
	v_fmac_f32_e32 v12, v103, v103
	v_add_f32_e32 v11, v11, v12
	ds_bpermute_b32 v13, v5, v11
	s_waitcnt lgkmcnt(0)
	v_add_f32_e32 v11, v11, v13
	ds_bpermute_b32 v13, v6, v11
	s_waitcnt lgkmcnt(0)
	v_add_f32_e32 v11, v11, v13
	ds_bpermute_b32 v13, v7, v11
	s_waitcnt lgkmcnt(0)
	v_add_f32_e32 v11, v11, v13
	ds_bpermute_b32 v13, v8, v11
	s_waitcnt lgkmcnt(0)
	v_add_f32_e32 v11, v11, v13
	ds_bpermute_b32 v13, v9, v11
	s_waitcnt lgkmcnt(0)
	v_add_f32_e32 v11, v11, v13
	ds_bpermute_b32 v13, v10, v11
	s_waitcnt lgkmcnt(0)
	v_add_f32_e32 v11, v11, v13
	s_mov_b64 exec, 1
	global_store_dword v4, v11, s[30:31]
	s_mov_b64 exec, -1
	s_add_u32 s17, s16, 0x3800
	s_mul_hi_u32 s18, s17, 0x1f07c2
	s_mul_i32 s19, s18, 0x840
	s_sub_u32 s19, s17, s19
	s_mov_b32 s37, 0
	s_mov_b64 s[20:21], s[32:33]
	s_cmp_lt_u32 s19, 48
	s_cbranch_scc0 .Linit_i7_a
	s_mov_b32 s37, 1
	s_branch .Linit_i7_ld

; __device__ __forceinline__ float shx(float v, int mask, int lane) { return __int_as_float(__builtin_amdgcn_ds_bpermute((lane ^ mask) << 2, __float_as_int(v))); }
; __device__ __forceinline__ unsigned pack2(float lo, float hi) { unsigned r; asm("v_cvt_pk_bf16_f32 %0, %1, %2" : "=v"(r) : "v"(lo), "v"(hi)); return r; }
; __device__ __forceinline__ void init_phase(int wv, PP P) {
;     ...
;     for (int row = blockIdx.x * 8 + w; row < MP; row += gridDim.x * 8) {
;         const int b = row / LP, pp = row % LP;
;         const float* src = pp < PADN ? nullptr : (pp < LEADR ? P->meta + (size_t)(pp - PADN) * D : P->x + ((size_t)b * SEQ + (pp - LEADR)) * D);
;         float ss = 0.f;
; #pragma unroll
;         for (int i = 0; i < 8; ++i) {
;             const int c = (i * 64 + lane) * 4; f32x4 v = (f32x4){0.f, 0.f, 0.f, 0.f}; if (src) v = *(const f32x4*)(src + c);
;             *(f32x4*)(hp + (size_t)row * D + c) = v; u32x2 o; o.x = pack2(v[0], v[1]); o.y = pack2(v[2], v[3]); *(u32x2*)(hb + (size_t)row * D + c) = o;
;             ss += v[0] * v[0] + v[1] * v[1] + v[2] * v[2] + v[3] * v[3];
;         }
; #pragma unroll
;         for (int o = 1; o < 64; o <<= 1) ss += shx(ss, o, lane);
;         if (lane == 0) rsq[row] = ss;
.Linit_p6:
	s_add_u32 s17, s16, 0x3000
	s_lshl_b32 s38, s17, 13
	s_add_u32 s24, s6, s38
	s_addc_u32 s25, s7, 0
	s_add_u32 s26, s24, 0x1000
	s_addc_u32 s27, s25, 0
	s_lshl_b32 s38, s17, 12
	s_add_u32 s28, s4, s38
	s_addc_u32 s29, s5, 0
	s_lshl_b32 s38, s17, 2
	s_add_u32 s30, s8, s38
	s_addc_u32 s31, s9, 0
	global_store_dwordx4 v2, v[40:43], s[24:25]
	v_cvt_pk_bf16_f32 v14, v40, v41
	v_cvt_pk_bf16_f32 v15, v42, v43
	v_mul_f32_e32 v12, v41, v41
	global_store_dwordx2 v3, v[14:15], s[28:29]
	v_fmac_f32_e32 v12, v40, v40
	v_fmac_f32_e32 v12, v42, v42
	v_fmac_f32_e32 v12, v43, v43
	v_mov_b32_e32 v11, v12
	global_store_dwordx4 v2, v[44:47], s[24:25] offset:1024
	v_cvt_pk_bf16_f32 v16, v44, v45
	v_cvt_pk_bf16_f32 v17, v46, v47
	v_mul_f32_e32 v12, v45, v45
	global_store_dwordx2 v3, v[16:17], s[28:29] offset:512
	v_fmac_f32_e32 v12, v44, v44
	v_fmac_f32_e32 v12, v46, v46
	v_fmac_f32_e32 v12, v47, v47
	v_add_f32_e32 v11, v11, v12
	global_store_dwordx4 v2, v[48:51], s[24:25] offset:2048
	v_cvt_pk_bf16_f32 v14, v48, v49
	v_cvt_pk_bf16_f32 v15, v50, v51
	v_mul_f32_e32 v12, v49, v49
	global_store_dwordx2 v3, v[14:15], s[28:29] offset:1024
	v_fmac_f32_e32 v12, v48, v48
	v_fmac_f32_e32 v12, v50, v50
	v_fmac_f32_e32 v12, v51, v51
	v_add_f32_e32 v11, v11, v12
	global_store_dwordx4 v2, v[52:55], s[24:25] offset:3072
	v_cvt_pk_bf16_f32 v16, v52, v53
	v_cvt_pk_bf16_f32 v17, v54, v55
	v_mul_f32_e32 v12, v53, v53
	global_store_dwordx2 v3, v[16:17], s[28:29] offset:1536
	v_fmac_f32_e32 v12, v52, v52
	v_fmac_f32_e32 v12, v54, v54
	v_fmac_f32_e32 v12, v55, v55
	v_add_f32_e32 v11, v11, v12
	global_store_dwordx4 v2, v[56:59], s[26:27]
	v_cvt_pk_bf16_f32 v14, v56, v57
	v_cvt_pk_bf16_f32 v15, v58, v59
	v_mul_f32_e32 v12, v57, v57
	global_store_dwordx2 v3, v[14:15], s[28:29] offset:2048
	v_fmac_f32_e32 v12, v56, v56
	v_fmac_f32_e32 v12, v58, v58
	v_fmac_f32_e32 v12, v59, v59
	v_add_f32_e32 v11, v11, v12
	global_store_dwordx4 v2, v[60:63], s[26:27] offset:1024
	v_cvt_pk_bf16_f32 v16, v60, v61
	v_cvt_pk_bf16_f32 v17, v62, v63
	v_mul_f32_e32 v12, v61, v61
	global_store_dwordx2 v3, v[16:17], s[28:29] offset:2560
	v_fmac_f32_e32 v12, v60, v60
	v_fmac_f32_e32 v12, v62, v62
	v_fmac_f32_e32 v12, v63, v63
	v_add_f32_e32 v11, v11, v12
	global_store_dwordx4 v2, v[64:67], s[26:27] offset:2048
	v_cvt_pk_bf16_f32 v14, v64, v65
	v_cvt_pk_bf16_f32 v15, v66, v67
	v_mul_f32_e32 v12, v65, v65
	global_store_dwordx2 v3, v[14:15], s[28:29] offset:3072
	v_fmac_f32_e32 v12, v64, v64
	v_fmac_f32_e32 v12, v66, v66
	v_fmac_f32_e32 v12, v67, v67
	v_add_f32_e32 v11, v11, v12
	global_store_dwordx4 v2, v[68:71], s[26:27] offset:3072
	v_cvt_pk_bf16_f32 v16, v68, v69
	v_cvt_pk_bf16_f32 v17, v70, v71
	v_mul_f32_e32 v12, v69, v69
	global_store_dwordx2 v3, v[16:17], s[28:29] offset:3584
	v_fmac_f32_e32 v12, v68, v68
	v_fmac_f32_e32 v12, v70, v70
	v_fmac_f32_e32 v12, v71, v71
	v_add_f32_e32 v11, v11, v12
	ds_bpermute_b32 v13, v5, v11
	s_waitcnt lgkmcnt(0)
	v_add_f32_e32 v11, v11, v13
	ds_bpermute_b32 v13, v6, v11
	s_waitcnt lgkmcnt(0)
	v_add_f32_e32 v11, v11, v13
	ds_bpermute_b32 v13, v7, v11
	s_waitcnt lgkmcnt(0)
	v_add_f32_e32 v11, v11, v13
	ds_bpermute_b32 v13, v8, v11
	s_waitcnt lgkmcnt(0)
	v_add_f32_e32 v11, v11, v13
	ds_bpermute_b32 v13, v9, v11
	s_waitcnt lgkmcnt(0)
	v_add_f32_e32 v11, v11, v13
	ds_bpermute_b32 v13, v10, v11
	s_waitcnt lgkmcnt(0)
	v_add_f32_e32 v11, v11, v13
	s_mov_b64 exec, 1
	global_store_dword v4, v11, s[30:31]
	s_mov_b64 exec, -1
	s_add_u32 s17, s16, 0x4000
	s_cmp_lt_u32 s16, 0x200
	s_cselect_b32 s17, s17, s16
	s_mul_hi_u32 s18, s17, 0x1f07c2
	s_mul_i32 s19, s18, 0x840
	s_sub_u32 s19, s17, s19
	s_mov_b32 s36, 0
	s_mov_b64 s[20:21], s[32:33]
	s_cmp_lt_u32 s19, 48
	s_cbranch_scc0 .Linit_i8_a
	s_mov_b32 s36, 1
	s_branch .Linit_i8_ld

; __device__ __forceinline__ float shx(float v, int mask, int lane) { return __int_as_float(__builtin_amdgcn_ds_bpermute((lane ^ mask) << 2, __float_as_int(v))); }
; __device__ __forceinline__ unsigned pack2(float lo, float hi) { unsigned r; asm("v_cvt_pk_bf16_f32 %0, %1, %2" : "=v"(r) : "v"(lo), "v"(hi)); return r; }
; __device__ __forceinline__ void init_phase(int wv, PP P) {
;     ...
;     for (int row = blockIdx.x * 8 + w; row < MP; row += gridDim.x * 8) {
;         const int b = row / LP, pp = row % LP;
;         const float* src = pp < PADN ? nullptr : (pp < LEADR ? P->meta + (size_t)(pp - PADN) * D : P->x + ((size_t)b * SEQ + (pp - LEADR)) * D);
;         float ss = 0.f;
; #pragma unroll
;         for (int i = 0; i < 8; ++i) {
;             const int c = (i * 64 + lane) * 4; f32x4 v = (f32x4){0.f, 0.f, 0.f, 0.f}; if (src) v = *(const f32x4*)(src + c);
;             *(f32x4*)(hp + (size_t)row * D + c) = v; u32x2 o; o.x = pack2(v[0], v[1]); o.y = pack2(v[2], v[3]); *(u32x2*)(hb + (size_t)row * D + c) = o;
;             ss += v[0] * v[0] + v[1] * v[1] + v[2] * v[2] + v[3] * v[3];
;         }
; #pragma unroll
;         for (int o = 1; o < 64; o <<= 1) ss += shx(ss, o, lane);
;         if (lane == 0) rsq[row] = ss;
.Linit_p7:
	s_add_u32 s17, s16, 0x3800
	s_lshl_b32 s38, s17, 13
	s_add_u32 s24, s6, s38
	s_addc_u32 s25, s7, 0
	s_add_u32 s26, s24, 0x1000
	s_addc_u32 s27, s25, 0
	s_lshl_b32 s38, s17, 12
	s_add_u32 s28, s4, s38
	s_addc_u32 s29, s5, 0
	s_lshl_b32 s38, s17, 2
	s_add_u32 s30, s8, s38
	s_addc_u32 s31, s9, 0
	global_store_dwordx4 v2, v[72:75], s[24:25]
	v_cvt_pk_bf16_f32 v14, v72, v73
	v_cvt_pk_bf16_f32 v15, v74, v75
	v_mul_f32_e32 v12, v73, v73
	global_store_dwordx2 v3, v[14:15], s[28:29]
	v_fmac_f32_e32 v12, v72, v72
	v_fmac_f32_e32 v12, v74, v74
	v_fmac_f32_e32 v12, v75, v75
	v_mov_b32_e32 v11, v12
	global_store_dwordx4 v2, v[76:79], s[24:25] offset:1024
	v_cvt_pk_bf16_f32 v16, v76, v77
	v_cvt_pk_bf16_f32 v17, v78, v79
	v_mul_f32_e32 v12, v77, v77
	global_store_dwordx2 v3, v[16:17], s[28:29] offset:512
	v_fmac_f32_e32 v12, v76, v76
	v_fmac_f32_e32 v12, v78, v78
	v_fmac_f32_e32 v12, v79, v79
	v_add_f32_e32 v11, v11, v12
	global_store_dwordx4 v2, v[80:83], s[24:25] offset:2048
	v_cvt_pk_bf16_f32 v14, v80, v81
	v_cvt_pk_bf16_f32 v15, v82, v83
	v_mul_f32_e32 v12, v81, v81
	global_store_dwordx2 v3, v[14:15], s[28:29] offset:1024
	v_fmac_f32_e32 v12, v80, v80
	v_fmac_f32_e32 v12, v82, v82
	v_fmac_f32_e32 v12, v83, v83
	v_add_f32_e32 v11, v11, v12
	global_store_dwordx4 v2, v[84:87], s[24:25] offset:3072
	v_cvt_pk_bf16_f32 v16, v84, v85
	v_cvt_pk_bf16_f32 v17, v86, v87
	v_mul_f32_e32 v12, v85, v85
	global_store_dwordx2 v3, v[16:17], s[28:29] offset:1536
	v_fmac_f32_e32 v12, v84, v84
	v_fmac_f32_e32 v12, v86, v86
	v_fmac_f32_e32 v12, v87, v87
	v_add_f32_e32 v11, v11, v12
	global_store_dwordx4 v2, v[88:91], s[26:27]
	v_cvt_pk_bf16_f32 v14, v88, v89
	v_cvt_pk_bf16_f32 v15, v90, v91
	v_mul_f32_e32 v12, v89, v89
	global_store_dwordx2 v3, v[14:15], s[28:29] offset:2048
	v_fmac_f32_e32 v12, v88, v88
	v_fmac_f32_e32 v12, v90, v90
	v_fmac_f32_e32 v12, v91, v91
	v_add_f32_e32 v11, v11, v12
	global_store_dwordx4 v2, v[92:95], s[26:27] offset:1024
	v_cvt_pk_bf16_f32 v16, v92, v93
	v_cvt_pk_bf16_f32 v17, v94, v95
	v_mul_f32_e32 v12, v93, v93
	global_store_dwordx2 v3, v[16:17], s[28:29] offset:2560
	v_fmac_f32_e32 v12, v92, v92
	v_fmac_f32_e32 v12, v94, v94
	v_fmac_f32_e32 v12, v95, v95
	v_add_f32_e32 v11, v11, v12
	global_store_dwordx4 v2, v[96:99], s[26:27] offset:2048
	v_cvt_pk_bf16_f32 v14, v96, v97
	v_cvt_pk_bf16_f32 v15, v98, v99
	v_mul_f32_e32 v12, v97, v97
	global_store_dwordx2 v3, v[14:15], s[28:29] offset:3072
	v_fmac_f32_e32 v12, v96, v96
	v_fmac_f32_e32 v12, v98, v98
	v_fmac_f32_e32 v12, v99, v99
	v_add_f32_e32 v11, v11, v12
	global_store_dwordx4 v2, v[100:103], s[26:27] offset:3072
	v_cvt_pk_bf16_f32 v16, v100, v101
	v_cvt_pk_bf16_f32 v17, v102, v103
	v_mul_f32_e32 v12, v101, v101
	global_store_dwordx2 v3, v[16:17], s[28:29] offset:3584
	v_fmac_f32_e32 v12, v100, v100
	v_fmac_f32_e32 v12, v102, v102
	v_fmac_f32_e32 v12, v103, v103
	v_add_f32_e32 v11, v11, v12
	ds_bpermute_b32 v13, v5, v11
	s_waitcnt lgkmcnt(0)
	v_add_f32_e32 v11, v11, v13
	ds_bpermute_b32 v13, v6, v11
	s_waitcnt lgkmcnt(0)
	v_add_f32_e32 v11, v11, v13
	ds_bpermute_b32 v13, v7, v11
	s_waitcnt lgkmcnt(0)
	v_add_f32_e32 v11, v11, v13
	ds_bpermute_b32 v13, v8, v11
	s_waitcnt lgkmcnt(0)
	v_add_f32_e32 v11, v11, v13
	ds_bpermute_b32 v13, v9, v11
	s_waitcnt lgkmcnt(0)
	v_add_f32_e32 v11, v11, v13
	ds_bpermute_b32 v13, v10, v11
	s_waitcnt lgkmcnt(0)
	v_add_f32_e32 v11, v11, v13
	s_mov_b64 exec, 1
	global_store_dword v4, v11, s[30:31]
	s_mov_b64 exec, -1
	s_waitcnt vmcnt(17)
	s_cmp_lt_u32 s16, 0x200
	s_cbranch_scc0 .Linit_done
	s_cmp_eq_u32 s36, 0
	s_cbranch_scc1 .Linit_p8
	v_mov_b32_e32 v40, 0
	v_mov_b32_e32 v41, 0
	v_mov_b32_e32 v42, 0
	v_mov_b32_e32 v43, 0
	v_mov_b32_e32 v44, 0
	v_mov_b32_e32 v45, 0
	v_mov_b32_e32 v46, 0
	v_mov_b32_e32 v47, 0
	v_mov_b32_e32 v48, 0
	v_mov_b32_e32 v49, 0
	v_mov_b32_e32 v50, 0
	v_mov_b32_e32 v51, 0
	v_mov_b32_e32 v52, 0
	v_mov_b32_e32 v53, 0
	v_mov_b32_e32 v54, 0
	v_mov_b32_e32 v55, 0
	v_mov_b32_e32 v56, 0
	v_mov_b32_e32 v57, 0
	v_mov_b32_e32 v58, 0
	v_mov_b32_e32 v59, 0
	v_mov_b32_e32 v60, 0
	v_mov_b32_e32 v61, 0
	v_mov_b32_e32 v62, 0
	v_mov_b32_e32 v63, 0
	v_mov_b32_e32 v64, 0
	v_mov_b32_e32 v65, 0
	v_mov_b32_e32 v66, 0
	v_mov_b32_e32 v67, 0
	v_mov_b32_e32 v68, 0
	v_mov_b32_e32 v69, 0
	v_mov_b32_e32 v70, 0
	v_mov_b32_e32 v71, 0
; __device__ __forceinline__ float shx(float v, int mask, int lane) { return __int_as_float(__builtin_amdgcn_ds_bpermute((lane ^ mask) << 2, __float_as_int(v))); }
; __device__ __forceinline__ unsigned pack2(float lo, float hi) { unsigned r; asm("v_cvt_pk_bf16_f32 %0, %1, %2" : "=v"(r) : "v"(lo), "v"(hi)); return r; }
; __device__ __forceinline__ void init_phase(int wv, PP P) {
;     ...
;     for (int row = blockIdx.x * 8 + w; row < MP; row += gridDim.x * 8) {
;         const int b = row / LP, pp = row % LP;
;         const float* src = pp < PADN ? nullptr : (pp < LEADR ? P->meta + (size_t)(pp - PADN) * D : P->x + ((size_t)b * SEQ + (pp - LEADR)) * D);
;         float ss = 0.f;
; #pragma unroll
;         for (int i = 0; i < 8; ++i) {
;             const int c = (i * 64 + lane) * 4; f32x4 v = (f32x4){0.f, 0.f, 0.f, 0.f}; if (src) v = *(const f32x4*)(src + c);
;             *(f32x4*)(hp + (size_t)row * D + c) = v; u32x2 o; o.x = pack2(v[0], v[1]); o.y = pack2(v[2], v[3]); *(u32x2*)(hb + (size_t)row * D + c) = o;
;             ss += v[0] * v[0] + v[1] * v[1] + v[2] * v[2] + v[3] * v[3];
;         }
; #pragma unroll
;         for (int o = 1; o < 64; o <<= 1) ss += shx(ss, o, lane);
;         if (lane == 0) rsq[row] = ss;
;     }
;     for (int i = blockIdx.x * 512 + tid; i < 4 * MP; i += gridDim.x * 512) rsq[MP + i] = 0.f;
.Linit_p8:
	s_add_u32 s17, s16, 0x4000
	s_lshl_b32 s38, s17, 13
	s_add_u32 s24, s6, s38
	s_addc_u32 s25, s7, 0
	s_add_u32 s26, s24, 0x1000
	s_addc_u32 s27, s25, 0
	s_lshl_b32 s38, s17, 12
	s_add_u32 s28, s4, s38
	s_addc_u32 s29, s5, 0
	s_lshl_b32 s38, s17, 2
	s_add_u32 s30, s8, s38
	s_addc_u32 s31, s9, 0
	global_store_dwordx4 v2, v[40:43], s[24:25]
	v_cvt_pk_bf16_f32 v14, v40, v41
	v_cvt_pk_bf16_f32 v15, v42, v43
	v_mul_f32_e32 v12, v41, v41
	global_store_dwordx2 v3, v[14:15], s[28:29]
	v_fmac_f32_e32 v12, v40, v40
	v_fmac_f32_e32 v12, v42, v42
	v_fmac_f32_e32 v12, v43, v43
	v_mov_b32_e32 v11, v12
	global_store_dwordx4 v2, v[44:47], s[24:25] offset:1024
	v_cvt_pk_bf16_f32 v16, v44, v45
	v_cvt_pk_bf16_f32 v17, v46, v47
	v_mul_f32_e32 v12, v45, v45
	global_store_dwordx2 v3, v[16:17], s[28:29] offset:512
	v_fmac_f32_e32 v12, v44, v44
	v_fmac_f32_e32 v12, v46, v46
	v_fmac_f32_e32 v12, v47, v47
	v_add_f32_e32 v11, v11, v12
	global_store_dwordx4 v2, v[48:51], s[24:25] offset:2048
	v_cvt_pk_bf16_f32 v14, v48, v49
	v_cvt_pk_bf16_f32 v15, v50, v51
	v_mul_f32_e32 v12, v49, v49
	global_store_dwordx2 v3, v[14:15], s[28:29] offset:1024
	v_fmac_f32_e32 v12, v48, v48
	v_fmac_f32_e32 v12, v50, v50
	v_fmac_f32_e32 v12, v51, v51
	v_add_f32_e32 v11, v11, v12
	global_store_dwordx4 v2, v[52:55], s[24:25] offset:3072
	v_cvt_pk_bf16_f32 v16, v52, v53
	v_cvt_pk_bf16_f32 v17, v54, v55
	v_mul_f32_e32 v12, v53, v53
	global_store_dwordx2 v3, v[16:17], s[28:29] offset:1536
	v_fmac_f32_e32 v12, v52, v52
	v_fmac_f32_e32 v12, v54, v54
	v_fmac_f32_e32 v12, v55, v55
	v_add_f32_e32 v11, v11, v12
	global_store_dwordx4 v2, v[56:59], s[26:27]
	v_cvt_pk_bf16_f32 v14, v56, v57
	v_cvt_pk_bf16_f32 v15, v58, v59
	v_mul_f32_e32 v12, v57, v57
	global_store_dwordx2 v3, v[14:15], s[28:29] offset:2048
	v_fmac_f32_e32 v12, v56, v56
	v_fmac_f32_e32 v12, v58, v58
	v_fmac_f32_e32 v12, v59, v59
	v_add_f32_e32 v11, v11, v12
	global_store_dwordx4 v2, v[60:63], s[26:27] offset:1024
	v_cvt_pk_bf16_f32 v16, v60, v61
	v_cvt_pk_bf16_f32 v17, v62, v63
	v_mul_f32_e32 v12, v61, v61
	global_store_dwordx2 v3, v[16:17], s[28:29] offset:2560
	v_fmac_f32_e32 v12, v60, v60
	v_fmac_f32_e32 v12, v62, v62
	v_fmac_f32_e32 v12, v63, v63
	v_add_f32_e32 v11, v11, v12
	global_store_dwordx4 v2, v[64:67], s[26:27] offset:2048
	v_cvt_pk_bf16_f32 v14, v64, v65
	v_cvt_pk_bf16_f32 v15, v66, v67
	v_mul_f32_e32 v12, v65, v65
	global_store_dwordx2 v3, v[14:15], s[28:29] offset:3072
	v_fmac_f32_e32 v12, v64, v64
	v_fmac_f32_e32 v12, v66, v66
	v_fmac_f32_e32 v12, v67, v67
	v_add_f32_e32 v11, v11, v12
	global_store_dwordx4 v2, v[68:71], s[26:27] offset:3072
	v_cvt_pk_bf16_f32 v16, v68, v69
	v_cvt_pk_bf16_f32 v17, v70, v71
	v_mul_f32_e32 v12, v69, v69
	global_store_dwordx2 v3, v[16:17], s[28:29] offset:3584
	v_fmac_f32_e32 v12, v68, v68
	v_fmac_f32_e32 v12, v70, v70
	v_fmac_f32_e32 v12, v71, v71
	v_add_f32_e32 v11, v11, v12
	ds_bpermute_b32 v13, v5, v11
	s_waitcnt lgkmcnt(0)
	v_add_f32_e32 v11, v11, v13
	ds_bpermute_b32 v13, v6, v11
	s_waitcnt lgkmcnt(0)
	v_add_f32_e32 v11, v11, v13
	ds_bpermute_b32 v13, v7, v11
	s_waitcnt lgkmcnt(0)
	v_add_f32_e32 v11, v11, v13
	ds_bpermute_b32 v13, v8, v11
	s_waitcnt lgkmcnt(0)
	v_add_f32_e32 v11, v11, v13
	ds_bpermute_b32 v13, v9, v11
	s_waitcnt lgkmcnt(0)
	v_add_f32_e32 v11, v11, v13
	ds_bpermute_b32 v13, v10, v11
	s_waitcnt lgkmcnt(0)
	v_add_f32_e32 v11, v11, v13
	s_mov_b64 exec, 1
	global_store_dword v4, v11, s[30:31]
	s_mov_b64 exec, -1
.Linit_done:
.LBB0_88:
	s_or_b64 exec, exec, s[14:15]
	v_lshl_add_u32 v2, s81, 9, v39
	s_mov_b32 s4, 0x10800
	v_cmp_gt_i32_e32 vcc, s4, v2
	s_and_saveexec_b64 s[4:5], vcc
	s_cbranch_execz .LBB0_91
	s_lshl_b32 s14, s48, 9
	s_mov_b64 s[10:11], 0
	s_waitcnt lgkmcnt(0)
	v_mov_b32_e32 v3, 0
	s_mov_b32 s15, 0x107ff
	v_mov_b32_e32 v4, v2

; __device__ __forceinline__ void convert_weight(int wv, const float* __restrict__ src, int ldsrc, int Ksrc, bf16_t* dst, int ldd, int koff, int ntn, const float* kscale, int mode, LAS float* tile, int pidx, int pcnt) {
;     ...
;     auto prefetch = [&](int t) {
;         const int tn = t % ntn, tk = t / ntn; const int n0 = tn * 64, k0 = tk * 128;
;         int scol = n0, nvalid = 64;
;         if (mode == 1) { if (n0 < 5632) scol = n0; else if (n0 < 13312) scol = n0 + 8; else if (n0 == 13312) { scol = 5632; nvalid = 8; } else { scol = 0; nvalid = 0; } }
; #pragma unroll
;         for (int i = 0; i < 4; ++i) { const int kk = kk0 + i * 32; v[i] = (f32x4){0.f, 0.f, 0.f, 0.f};
;             if (n4 < nvalid) v[i] = *(const f32x4*)(src + (size_t)(k0 + kk) * ldsrc + scol + n4);
;             ks[i] = kscale ? kscale[k0 + kk] : 1.0f; }
;     };
;     int t = pidx; int buf = 0;
;     if (t < total) prefetch(t);
; __device__ __forceinline__ void convert_layer(int wv, PP P, int L, int mask, LAS float* tile, int pidx, int pcnt) {
;     ...
;         convert_weight(wv, P->w_br_a + (size_t)L * 512 * D, D, 512, wbr, D, 0, D / 64, nullptr, 0, tile, pidx, pcnt);
.LBB0_192:
	v_cndmask_b32_e64 v0, 0, 1, s[10:11]
	v_cmp_ne_u32_e64 s[4:5], 1, v0
	s_andn2_b64 vcc, exec, s[10:11]
	s_nop 0
	v_writelane_b32 v254, s4, 30
	s_nop 1
	v_writelane_b32 v254, s5, 31
	s_cbranch_vccnz .LBB0_223
	s_mov_b32 s6, s81
	v_readlane_b32 s4, v254, 3
	s_cmp_lt_i32 s6, s4
	v_readlane_b32 s8, v254, 1
	s_cselect_b64 s[4:5], -1, 0
	v_readlane_b32 s9, v254, 2
	s_or_b64 s[4:5], s[8:9], s[4:5]
	s_and_b64 vcc, exec, s[4:5]
	s_cbranch_vccnz .LBB0_223
	s_mov_b64 s[4:5], s[0:1]
	v_readlane_b32 s7, v254, 3
	s_sub_i32 s20, s6, s7
	s_load_dwordx2 s[6:7], s[4:5], 0x98
	s_cmpk_lt_i32 s20, 0x80
	s_mov_b32 s16, s95
	v_mov_b32_e32 v0, v3
	s_cselect_b64 s[8:9], -1, 0
	s_cmpk_gt_i32 s20, 0x7f
	s_cbranch_scc1 .LBB0_201
	v_mbcnt_lo_u32_b32 v0, -1, v0
	v_mbcnt_hi_u32_b32 v20, -1, v0
	s_waitcnt lgkmcnt(0)
	s_add_u32 s12, s6, 0x4200000
	v_lshl_or_b32 v21, s16, 6, v20
	s_sext_i32_i16 s16, s20
	s_addc_u32 s13, s7, 0
	s_bfe_u32 s16, s16, 0x5001a
	s_add_i32 s16, s20, s16
	s_sext_i32_i16 s17, s16
	s_load_dwordx2 s[14:15], s[4:5], 0x48
	v_ashrrev_i32_e32 v22, 4, v21
	s_and_b32 s16, s16, 0xffe0
	s_lshl_b32 s17, s17, 2
	v_lshlrev_b32_e32 v0, 2, v20
	s_sub_i32 s16, s20, s16
	s_and_b32 s18, s17, 0xffffff80
	v_add_u32_e32 v23, 32, v22
	s_waitcnt vmcnt(0)
	v_add_u32_e32 v24, 64, v22
	v_add_u32_e32 v25, 0x60, v22
	v_and_b32_e32 v2, 60, v0
	s_sext_i32_i16 s16, s16
	v_add_u32_e32 v0, s18, v22
	v_add_u32_e32 v6, s18, v23
	v_add_u32_e32 v12, s18, v24
	v_add_u32_e32 v14, s18, v25
	s_lshl_b32 s16, s16, 6
	v_ashrrev_i32_e32 v1, 31, v0
	v_ashrrev_i32_e32 v7, 31, v6
	v_ashrrev_i32_e32 v13, 31, v12
	v_ashrrev_i32_e32 v15, 31, v14
	s_ashr_i32 s17, s16, 31
	v_lshlrev_b64 v[0:1], 13, v[0:1]
	v_lshlrev_b64 v[6:7], 13, v[6:7]
	v_lshlrev_b64 v[12:13], 13, v[12:13]
	v_lshlrev_b64 v[14:15], 13, v[14:15]
	s_waitcnt lgkmcnt(0)
	v_lshl_add_u64 v[0:1], s[14:15], 0, v[0:1]
	s_lshl_b64 s[16:17], s[16:17], 2
	v_lshl_add_u64 v[6:7], s[14:15], 0, v[6:7]
	v_lshl_add_u64 v[12:13], s[14:15], 0, v[12:13]
	v_lshl_add_u64 v[14:15], s[14:15], 0, v[14:15]
	v_lshl_add_u64 v[4:5], v[0:1], 0, s[16:17]
	v_lshlrev_b32_e32 v0, 2, v2
	v_mov_b32_e32 v1, v3
	v_lshl_add_u64 v[6:7], v[6:7], 0, s[16:17]
	v_lshl_add_u64 v[12:13], v[12:13], 0, s[16:17]
	v_lshl_add_u64 v[14:15], v[14:15], 0, s[16:17]
	v_lshl_add_u64 v[4:5], v[4:5], 0, v[0:1]
	v_lshl_add_u64 v[8:9], v[6:7], 0, v[0:1]
	v_lshl_add_u64 v[12:13], v[12:13], 0, v[0:1]
	v_lshl_add_u64 v[16:17], v[14:15], 0, v[0:1]
	global_load_dwordx4 v[4:7], v[4:5], off
	s_nop 0
	global_load_dwordx4 v[8:11], v[8:9], off
	s_nop 0
	global_load_dwordx4 v[12:15], v[12:13], off
	s_nop 0
	global_load_dwordx4 v[16:19], v[16:17], off
	v_lshlrev_b32_e32 v20, 4, v20
	v_and_b32_e32 v28, 0x70, v20
	v_ashrrev_i32_e32 v1, 3, v21
	v_mul_u32_u24_e32 v26, 0x104, v28
	v_mul_lo_u32 v27, v22, s87
	s_lshl_b32 s23, s20, 6
	s_lshl_b32 s21, s3, 6
	s_mov_b32 s22, 0
	v_lshlrev_b32_e32 v20, 2, v2
	v_lshlrev_b32_e32 v2, 1, v28
	s_mov_b32 s26, s20
	s_waitcnt vmcnt(0)
	s_branch .LBB0_197

; #define LAS __attribute__((address_space(3)))
; __device__ __forceinline__ void lds_barrier() { asm volatile("s_waitcnt lgkmcnt(0)" ::: "memory"); __builtin_amdgcn_s_barrier(); asm volatile("" ::: "memory"); }
; __device__ __forceinline__ void convert_weight(int wv, const float* __restrict__ src, int ldsrc, int Ksrc, bf16_t* dst, int ldd, int koff, int ntn, const float* kscale, int mode, LAS float* tile, int pidx, int pcnt) {
;     ...
;     for (; t < total; t += G) {
;         LAS float* tl = tile + buf * (128 * 65);
; #pragma unroll
;         for (int i = 0; i < 4; ++i) { const int kk = kk0 + i * 32;
;             tl[kk * 65 + n4 + 0] = v[i][0] * ks[i]; tl[kk * 65 + n4 + 1] = v[i][1] * ks[i]; tl[kk * 65 + n4 + 2] = v[i][2] * ks[i]; tl[kk * 65 + n4 + 3] = v[i][3] * ks[i]; }
;         lds_barrier();
;         const int tn = t % ntn, tk = t / ntn; const int n0 = tn * 64, k0 = tk * 128;
;         if (t + G < total) prefetch(t + G);
.LBB0_197:
	s_mul_i32 s16, s22, 0x8200
	s_add_i32 s27, s16, 0
	v_add3_u32 v21, s27, v0, v27
	v_add_u32_e32 v28, 0x2080, v21
	s_waitcnt vmcnt(2)
	ds_write2_b32 v21, v4, v5 offset1:1
	ds_write2_b32 v21, v6, v7 offset0:2 offset1:3
	ds_write2_b32 v28, v8, v9 offset1:1
	v_add_u32_e32 v28, 0x2088, v21
	ds_write2_b32 v28, v10, v11 offset1:1
	v_add_u32_e32 v28, 0x4100, v21
	ds_write2_b32 v28, v12, v13 offset1:1
	v_add_u32_e32 v28, 0x4108, v21
	ds_write2_b32 v28, v14, v15 offset1:1
	v_add_u32_e32 v28, 0x6180, v21
	v_add_u32_e32 v21, 0x6188, v21
	ds_write2_b32 v28, v16, v17 offset1:1
	ds_write2_b32 v21, v18, v19 offset1:1
	s_waitcnt lgkmcnt(0)
	s_barrier
	s_add_i32 s24, s26, s3
	s_cmpk_gt_i32 s24, 0x7f
	s_cselect_b64 s[16:17], -1, 0
	s_cmpk_lt_i32 s24, 0x80
	s_mov_b64 s[18:19], -1
	s_cbranch_scc1 .LBB0_199
	s_add_i32 s25, s23, s21
	s_mov_b64 s[18:19], 0

; __device__ __forceinline__ void convert_weight(int wv, const float* __restrict__ src, int ldsrc, int Ksrc, bf16_t* dst, int ldd, int koff, int ntn, const float* kscale, int mode, LAS float* tile, int pidx, int pcnt) {
;     ...
;     auto prefetch = [&](int t) {
;         const int tn = t % ntn, tk = t / ntn; const int n0 = tn * 64, k0 = tk * 128;
;         int scol = n0, nvalid = 64;
;         if (mode == 1) { if (n0 < 5632) scol = n0; else if (n0 < 13312) scol = n0 + 8; else if (n0 == 13312) { scol = 5632; nvalid = 8; } else { scol = 0; nvalid = 0; } }
; #pragma unroll
;         for (int i = 0; i < 4; ++i) { const int kk = kk0 + i * 32; v[i] = (f32x4){0.f, 0.f, 0.f, 0.f};
;             if (n4 < nvalid) v[i] = *(const f32x4*)(src + (size_t)(k0 + kk) * ldsrc + scol + n4);
;             ks[i] = kscale ? kscale[k0 + kk] : 1.0f; }
;     };
;     int t = pidx; int buf = 0;
;     if (t < total) prefetch(t);
; __device__ __forceinline__ void convert_layer(int wv, PP P, int L, int mask, LAS float* tile, int pidx, int pcnt) {
;     ...
;         convert_weight(wv, P->w_br_m + (size_t)L * 1024 * D, D, 1024, wbr, D, 512, D / 64, nullptr, 0, tile, pidx, pcnt);
.LBB0_201:
	s_mov_b32 s14, s95
	v_mov_b32_e32 v0, v3
	s_cmpk_gt_i32 s20, 0xff
	s_waitcnt vmcnt(0) lgkmcnt(0)
	s_barrier
	s_cbranch_scc1 .LBB0_208
	v_mbcnt_lo_u32_b32 v0, -1, v0
	v_mbcnt_hi_u32_b32 v20, -1, v0
	v_lshl_or_b32 v21, s14, 6, v20
	s_ashr_i32 s14, s20, 31
	s_lshr_b32 s14, s14, 27
	s_add_i32 s15, s20, s14
	s_load_dwordx2 s[12:13], s[4:5], 0x50
	v_ashrrev_i32_e32 v22, 4, v21
	s_and_b32 s14, s15, 0x3ffffe0
	s_lshl_b32 s15, s15, 2
	v_lshlrev_b32_e32 v0, 2, v20
	s_and_b32 s16, s15, 0xffffff80
	v_add_u32_e32 v23, 32, v22
	v_add_u32_e32 v24, 64, v22
	v_add_u32_e32 v25, 0x60, v22
	v_and_b32_e32 v2, 60, v0
	s_sub_i32 s14, s20, s14
	v_add_u32_e32 v0, s16, v22
	v_add_u32_e32 v6, s16, v23
	v_add_u32_e32 v12, s16, v24
	v_add_u32_e32 v14, s16, v25
	s_lshl_b32 s14, s14, 6
	v_ashrrev_i32_e32 v1, 31, v0
	v_ashrrev_i32_e32 v7, 31, v6
	v_ashrrev_i32_e32 v13, 31, v12
	v_ashrrev_i32_e32 v15, 31, v14
	s_ashr_i32 s15, s14, 31
	v_lshlrev_b64 v[0:1], 13, v[0:1]
	v_lshlrev_b64 v[6:7], 13, v[6:7]
	v_lshlrev_b64 v[12:13], 13, v[12:13]
	v_lshlrev_b64 v[14:15], 13, v[14:15]
	s_waitcnt lgkmcnt(0)
	v_lshl_add_u64 v[0:1], s[12:13], 0, v[0:1]
	s_lshl_b64 s[14:15], s[14:15], 2
	v_lshl_add_u64 v[6:7], s[12:13], 0, v[6:7]
	v_lshl_add_u64 v[12:13], s[12:13], 0, v[12:13]
	v_lshl_add_u64 v[14:15], s[12:13], 0, v[14:15]
	v_lshl_add_u64 v[4:5], v[0:1], 0, s[14:15]
	v_lshlrev_b32_e32 v0, 2, v2
	v_mov_b32_e32 v1, v3
	v_lshl_add_u64 v[6:7], v[6:7], 0, s[14:15]
	v_lshl_add_u64 v[12:13], v[12:13], 0, s[14:15]
	v_lshl_add_u64 v[14:15], v[14:15], 0, s[14:15]
	v_lshl_add_u64 v[4:5], v[4:5], 0, v[0:1]
	v_lshl_add_u64 v[8:9], v[6:7], 0, v[0:1]
	v_lshl_add_u64 v[12:13], v[12:13], 0, v[0:1]
	v_lshl_add_u64 v[16:17], v[14:15], 0, v[0:1]
	global_load_dwordx4 v[4:7], v[4:5], off
	s_nop 0
	global_load_dwordx4 v[8:11], v[8:9], off
	s_nop 0
	global_load_dwordx4 v[12:15], v[12:13], off
	s_nop 0
	global_load_dwordx4 v[16:19], v[16:17], off
	v_lshlrev_b32_e32 v20, 4, v20
	v_and_b32_e32 v28, 0x70, v20
	s_add_u32 s14, s6, 0x4200400
	v_ashrrev_i32_e32 v1, 3, v21
	v_mul_u32_u24_e32 v26, 0x104, v28
	s_addc_u32 s15, s7, 0
	v_mul_lo_u32 v27, v22, s87
	s_lshl_b32 s23, s20, 6
	s_lshl_b32 s21, s3, 6
	s_mov_b32 s22, 0
	v_lshlrev_b32_e32 v20, 2, v2
	v_lshlrev_b32_e32 v2, 1, v28
	s_mov_b32 s26, s20
	s_waitcnt vmcnt(0)
	s_branch .LBB0_204

; #define LAS __attribute__((address_space(3)))
; __device__ __forceinline__ void lds_barrier() { asm volatile("s_waitcnt lgkmcnt(0)" ::: "memory"); __builtin_amdgcn_s_barrier(); asm volatile("" ::: "memory"); }
; __device__ __forceinline__ void convert_weight(int wv, const float* __restrict__ src, int ldsrc, int Ksrc, bf16_t* dst, int ldd, int koff, int ntn, const float* kscale, int mode, LAS float* tile, int pidx, int pcnt) {
;     ...
;     for (; t < total; t += G) {
;         LAS float* tl = tile + buf * (128 * 65);
; #pragma unroll
;         for (int i = 0; i < 4; ++i) { const int kk = kk0 + i * 32;
;             tl[kk * 65 + n4 + 0] = v[i][0] * ks[i]; tl[kk * 65 + n4 + 1] = v[i][1] * ks[i]; tl[kk * 65 + n4 + 2] = v[i][2] * ks[i]; tl[kk * 65 + n4 + 3] = v[i][3] * ks[i]; }
;         lds_barrier();
;         const int tn = t % ntn, tk = t / ntn; const int n0 = tn * 64, k0 = tk * 128;
;         if (t + G < total) prefetch(t + G);
.LBB0_204:
	s_mul_i32 s16, s22, 0x8200
	s_add_i32 s27, s16, 0
	v_add3_u32 v21, s27, v0, v27
	v_add_u32_e32 v28, 0x2080, v21
	s_waitcnt vmcnt(2)
	ds_write2_b32 v21, v4, v5 offset1:1
	ds_write2_b32 v21, v6, v7 offset0:2 offset1:3
	s_waitcnt vmcnt(2)
	ds_write2_b32 v28, v8, v9 offset1:1
	v_add_u32_e32 v28, 0x2088, v21
	ds_write2_b32 v28, v10, v11 offset1:1
	v_add_u32_e32 v28, 0x4100, v21
	s_waitcnt vmcnt(2)
	ds_write2_b32 v28, v12, v13 offset1:1
	v_add_u32_e32 v28, 0x4108, v21
	ds_write2_b32 v28, v14, v15 offset1:1
	v_add_u32_e32 v28, 0x6180, v21
	v_add_u32_e32 v21, 0x6188, v21
	s_waitcnt vmcnt(2)
	ds_write2_b32 v28, v16, v17 offset1:1
	ds_write2_b32 v21, v18, v19 offset1:1
	s_waitcnt lgkmcnt(0)
	s_barrier
	s_add_i32 s24, s26, s3
	s_cmpk_gt_i32 s24, 0xff
	s_cselect_b64 s[16:17], -1, 0
	s_cmpk_lt_i32 s24, 0x100
	s_mov_b64 s[18:19], -1
	s_cbranch_scc1 .LBB0_206
	s_add_i32 s25, s23, s21
	s_mov_b64 s[18:19], 0

; __device__ __forceinline__ void convert_weight(int wv, const float* __restrict__ src, int ldsrc, int Ksrc, bf16_t* dst, int ldd, int koff, int ntn, const float* kscale, int mode, LAS float* tile, int pidx, int pcnt) {
;     ...
;     auto prefetch = [&](int t) {
;         const int tn = t % ntn, tk = t / ntn; const int n0 = tn * 64, k0 = tk * 128;
;         int scol = n0, nvalid = 64;
;         if (mode == 1) { if (n0 < 5632) scol = n0; else if (n0 < 13312) scol = n0 + 8; else if (n0 == 13312) { scol = 5632; nvalid = 8; } else { scol = 0; nvalid = 0; } }
; #pragma unroll
;         for (int i = 0; i < 4; ++i) { const int kk = kk0 + i * 32; v[i] = (f32x4){0.f, 0.f, 0.f, 0.f};
;             if (n4 < nvalid) v[i] = *(const f32x4*)(src + (size_t)(k0 + kk) * ldsrc + scol + n4);
;             ks[i] = kscale ? kscale[k0 + kk] : 1.0f; }
;     };
;     int t = pidx; int buf = 0;
;     if (t < total) prefetch(t);
; __device__ __forceinline__ void convert_layer(int wv, PP P, int L, int mask, LAS float* tile, int pidx, int pcnt) {
;     ...
;         convert_weight(wv, P->w_br_d + (size_t)L * 512 * D, D, 512, wbr, D, 1536, D / 64, nullptr, 0, tile, pidx, pcnt);
.LBB0_208:
	s_mov_b32 s12, s95
	v_mov_b32_e32 v0, v3
	s_andn2_b64 vcc, exec, s[8:9]
	s_barrier
	s_cbranch_vccnz .LBB0_215
	v_mbcnt_lo_u32_b32 v0, -1, v0
	v_mbcnt_hi_u32_b32 v20, -1, v0
	v_lshl_or_b32 v21, s12, 6, v20
	s_ashr_i32 s12, s20, 31
	s_lshr_b32 s12, s12, 27
	s_add_i32 s13, s20, s12
	s_load_dwordx2 s[8:9], s[4:5], 0x58
	v_ashrrev_i32_e32 v22, 4, v21
	s_and_b32 s12, s13, 0x3ffffe0
	s_lshl_b32 s13, s13, 2
	v_lshlrev_b32_e32 v0, 2, v20
	s_and_b32 s14, s13, 0xffffff80
	v_add_u32_e32 v23, 32, v22
	v_add_u32_e32 v24, 64, v22
	v_add_u32_e32 v25, 0x60, v22
	v_and_b32_e32 v2, 60, v0
	s_sub_i32 s12, s20, s12
	v_add_u32_e32 v0, s14, v22
	s_waitcnt vmcnt(5)
	v_add_u32_e32 v6, s14, v23
	s_waitcnt vmcnt(3)
	v_add_u32_e32 v12, s14, v24
	v_add_u32_e32 v14, s14, v25
	s_lshl_b32 s12, s12, 6
	v_ashrrev_i32_e32 v1, 31, v0
	v_ashrrev_i32_e32 v7, 31, v6
	v_ashrrev_i32_e32 v13, 31, v12
	v_ashrrev_i32_e32 v15, 31, v14
	s_ashr_i32 s13, s12, 31
	v_lshlrev_b64 v[0:1], 13, v[0:1]
	v_lshlrev_b64 v[6:7], 13, v[6:7]
	v_lshlrev_b64 v[12:13], 13, v[12:13]
	v_lshlrev_b64 v[14:15], 13, v[14:15]
	s_waitcnt lgkmcnt(0)
	v_lshl_add_u64 v[0:1], s[8:9], 0, v[0:1]
	s_lshl_b64 s[12:13], s[12:13], 2
	v_lshl_add_u64 v[6:7], s[8:9], 0, v[6:7]
	v_lshl_add_u64 v[12:13], s[8:9], 0, v[12:13]
	v_lshl_add_u64 v[14:15], s[8:9], 0, v[14:15]
	v_lshl_add_u64 v[4:5], v[0:1], 0, s[12:13]
	v_lshlrev_b32_e32 v0, 2, v2
	v_mov_b32_e32 v1, v3
	v_lshl_add_u64 v[6:7], v[6:7], 0, s[12:13]
	v_lshl_add_u64 v[12:13], v[12:13], 0, s[12:13]
	v_lshl_add_u64 v[14:15], v[14:15], 0, s[12:13]
	v_lshl_add_u64 v[4:5], v[4:5], 0, v[0:1]
	v_lshl_add_u64 v[8:9], v[6:7], 0, v[0:1]
	v_lshl_add_u64 v[12:13], v[12:13], 0, v[0:1]
	s_waitcnt vmcnt(2)
	v_lshl_add_u64 v[16:17], v[14:15], 0, v[0:1]
	global_load_dwordx4 v[4:7], v[4:5], off
	s_nop 0
	global_load_dwordx4 v[8:11], v[8:9], off
	s_nop 0
	global_load_dwordx4 v[12:15], v[12:13], off
	s_nop 0
	global_load_dwordx4 v[16:19], v[16:17], off
	v_lshlrev_b32_e32 v20, 4, v20
	v_and_b32_e32 v28, 0x70, v20
	s_add_u32 s12, s6, 0x4200c00
	v_ashrrev_i32_e32 v1, 3, v21
	v_mul_u32_u24_e32 v26, 0x104, v28
	s_addc_u32 s13, s7, 0
	v_mul_lo_u32 v27, v22, s87
	s_lshl_b32 s21, s20, 6
	s_lshl_b32 s18, s3, 6
	s_mov_b32 s19, 0
	v_lshlrev_b32_e32 v20, 2, v2
	v_lshlrev_b32_e32 v2, 1, v28
	s_mov_b32 s24, s20
	s_waitcnt vmcnt(0)
	s_branch .LBB0_211

; #define LAS __attribute__((address_space(3)))
; __device__ __forceinline__ void lds_barrier() { asm volatile("s_waitcnt lgkmcnt(0)" ::: "memory"); __builtin_amdgcn_s_barrier(); asm volatile("" ::: "memory"); }
; __device__ __forceinline__ void convert_weight(int wv, const float* __restrict__ src, int ldsrc, int Ksrc, bf16_t* dst, int ldd, int koff, int ntn, const float* kscale, int mode, LAS float* tile, int pidx, int pcnt) {
;     ...
;     for (; t < total; t += G) {
;         LAS float* tl = tile + buf * (128 * 65);
; #pragma unroll
;         for (int i = 0; i < 4; ++i) { const int kk = kk0 + i * 32;
;             tl[kk * 65 + n4 + 0] = v[i][0] * ks[i]; tl[kk * 65 + n4 + 1] = v[i][1] * ks[i]; tl[kk * 65 + n4 + 2] = v[i][2] * ks[i]; tl[kk * 65 + n4 + 3] = v[i][3] * ks[i]; }
;         lds_barrier();
;         const int tn = t % ntn, tk = t / ntn; const int n0 = tn * 64, k0 = tk * 128;
;         if (t + G < total) prefetch(t + G);
.LBB0_211:
	s_mul_i32 s14, s19, 0x8200
	s_add_i32 s25, s14, 0
	v_add3_u32 v21, s25, v0, v27
	v_add_u32_e32 v28, 0x2080, v21
	s_waitcnt vmcnt(2)
	ds_write2_b32 v21, v4, v5 offset1:1
	ds_write2_b32 v21, v6, v7 offset0:2 offset1:3
	s_waitcnt vmcnt(2)
	ds_write2_b32 v28, v8, v9 offset1:1
	v_add_u32_e32 v28, 0x2088, v21
	ds_write2_b32 v28, v10, v11 offset1:1
	v_add_u32_e32 v28, 0x4100, v21
	s_waitcnt vmcnt(2)
	ds_write2_b32 v28, v12, v13 offset1:1
	v_add_u32_e32 v28, 0x4108, v21
	ds_write2_b32 v28, v14, v15 offset1:1
	v_add_u32_e32 v28, 0x6180, v21
	v_add_u32_e32 v21, 0x6188, v21
	s_waitcnt vmcnt(2)
	ds_write2_b32 v28, v16, v17 offset1:1
	ds_write2_b32 v21, v18, v19 offset1:1
	s_waitcnt lgkmcnt(0)
	s_barrier
	s_add_i32 s22, s24, s3
	s_cmpk_gt_i32 s22, 0x7f
	s_cselect_b64 s[14:15], -1, 0
	s_cmpk_lt_i32 s22, 0x80
	s_mov_b64 s[16:17], -1
	s_cbranch_scc1 .LBB0_213
	s_add_i32 s23, s21, s18
	s_mov_b64 s[16:17], 0

; __device__ __forceinline__ void convert_weight(int wv, const float* __restrict__ src, int ldsrc, int Ksrc, bf16_t* dst, int ldd, int koff, int ntn, const float* kscale, int mode, LAS float* tile, int pidx, int pcnt) {
;     ...
;     auto prefetch = [&](int t) {
;         const int tn = t % ntn, tk = t / ntn; const int n0 = tn * 64, k0 = tk * 128;
;         int scol = n0, nvalid = 64;
;         if (mode == 1) { if (n0 < 5632) scol = n0; else if (n0 < 13312) scol = n0 + 8; else if (n0 == 13312) { scol = 5632; nvalid = 8; } else { scol = 0; nvalid = 0; } }
; #pragma unroll
;         for (int i = 0; i < 4; ++i) { const int kk = kk0 + i * 32; v[i] = (f32x4){0.f, 0.f, 0.f, 0.f};
;             if (n4 < nvalid) v[i] = *(const f32x4*)(src + (size_t)(k0 + kk) * ldsrc + scol + n4);
;             ks[i] = kscale ? kscale[k0 + kk] : 1.0f; }
;     };
;     int t = pidx; int buf = 0;
;     if (t < total) prefetch(t);
; __device__ __forceinline__ void convert_layer(int wv, PP P, int L, int mask, LAS float* tile, int pidx, int pcnt) {
;     ...
;     if (mask & 4) convert_weight(wv, P->w_out + (size_t)L * D * D, D, D, (bf16_t*)(dob + DO_WOUT), D, 0, D / 64, nullptr, 0, tile, pidx, pcnt);
.LBB0_215:
	s_mov_b32 s8, s95
	v_mov_b32_e32 v0, v3
	s_cmpk_gt_i32 s20, 0x1ff
	s_barrier
	s_cbranch_scc1 .LBB0_222
	v_mbcnt_lo_u32_b32 v0, -1, v0
	s_add_u32 s6, s6, 0x4a00000
	v_mbcnt_hi_u32_b32 v20, -1, v0
	s_addc_u32 s7, s7, 0
	v_lshl_or_b32 v21, s8, 6, v20
	s_ashr_i32 s8, s20, 31
	s_lshr_b32 s8, s8, 27
	s_add_i32 s9, s20, s8
	s_load_dwordx2 s[4:5], s[4:5], 0x60
	v_ashrrev_i32_e32 v22, 4, v21
	s_and_b32 s8, s9, 0x3ffffe0
	s_lshl_b32 s9, s9, 2
	v_lshlrev_b32_e32 v0, 2, v20
	s_and_b32 s12, s9, 0xffffff80
	v_add_u32_e32 v23, 32, v22
	v_add_u32_e32 v24, 64, v22
	v_add_u32_e32 v25, 0x60, v22
	v_and_b32_e32 v2, 60, v0
	s_sub_i32 s8, s20, s8
	v_add_u32_e32 v0, s12, v22
	s_waitcnt vmcnt(5)
	v_add_u32_e32 v6, s12, v23
	s_waitcnt vmcnt(3)
	v_add_u32_e32 v12, s12, v24
	v_add_u32_e32 v14, s12, v25
	s_lshl_b32 s8, s8, 6
	v_ashrrev_i32_e32 v1, 31, v0
	v_ashrrev_i32_e32 v7, 31, v6
	v_ashrrev_i32_e32 v13, 31, v12
	v_ashrrev_i32_e32 v15, 31, v14
	s_ashr_i32 s9, s8, 31
	v_lshlrev_b64 v[0:1], 13, v[0:1]
	v_lshlrev_b64 v[6:7], 13, v[6:7]
	v_lshlrev_b64 v[12:13], 13, v[12:13]
	v_lshlrev_b64 v[14:15], 13, v[14:15]
	s_waitcnt lgkmcnt(0)
	v_lshl_add_u64 v[0:1], s[4:5], 0, v[0:1]
	s_lshl_b64 s[8:9], s[8:9], 2
	v_lshl_add_u64 v[6:7], s[4:5], 0, v[6:7]
	v_lshl_add_u64 v[12:13], s[4:5], 0, v[12:13]
	v_lshl_add_u64 v[14:15], s[4:5], 0, v[14:15]
	v_lshl_add_u64 v[4:5], v[0:1], 0, s[8:9]
	v_lshlrev_b32_e32 v0, 2, v2
	v_mov_b32_e32 v1, v3
	v_lshl_add_u64 v[6:7], v[6:7], 0, s[8:9]
	v_lshl_add_u64 v[12:13], v[12:13], 0, s[8:9]
	v_lshl_add_u64 v[14:15], v[14:15], 0, s[8:9]
	v_lshl_add_u64 v[4:5], v[4:5], 0, v[0:1]
	v_lshl_add_u64 v[8:9], v[6:7], 0, v[0:1]
	v_lshl_add_u64 v[12:13], v[12:13], 0, v[0:1]
	s_waitcnt vmcnt(2)
	v_lshl_add_u64 v[16:17], v[14:15], 0, v[0:1]
	global_load_dwordx4 v[4:7], v[4:5], off
	s_nop 0
	global_load_dwordx4 v[8:11], v[8:9], off
	s_nop 0
	global_load_dwordx4 v[12:15], v[12:13], off
	s_nop 0
	global_load_dwordx4 v[16:19], v[16:17], off
	v_lshlrev_b32_e32 v20, 4, v20
	v_and_b32_e32 v28, 0x70, v20
	v_ashrrev_i32_e32 v1, 3, v21
	v_mul_u32_u24_e32 v26, 0x104, v28
	v_mul_lo_u32 v27, v22, s87
	s_lshl_b32 s16, s20, 6
	s_lshl_b32 s14, s3, 6
	s_mov_b32 s15, 0
	v_lshlrev_b32_e32 v20, 2, v2
	v_lshlrev_b32_e32 v2, 1, v28
	s_waitcnt vmcnt(0)
	s_branch .LBB0_218

; #define LAS __attribute__((address_space(3)))
; __device__ __forceinline__ void lds_barrier() { asm volatile("s_waitcnt lgkmcnt(0)" ::: "memory"); __builtin_amdgcn_s_barrier(); asm volatile("" ::: "memory"); }
; __device__ __forceinline__ void convert_weight(int wv, const float* __restrict__ src, int ldsrc, int Ksrc, bf16_t* dst, int ldd, int koff, int ntn, const float* kscale, int mode, LAS float* tile, int pidx, int pcnt) {
;     ...
;     for (; t < total; t += G) {
;         LAS float* tl = tile + buf * (128 * 65);
; #pragma unroll
;         for (int i = 0; i < 4; ++i) { const int kk = kk0 + i * 32;
;             tl[kk * 65 + n4 + 0] = v[i][0] * ks[i]; tl[kk * 65 + n4 + 1] = v[i][1] * ks[i]; tl[kk * 65 + n4 + 2] = v[i][2] * ks[i]; tl[kk * 65 + n4 + 3] = v[i][3] * ks[i]; }
;         lds_barrier();
;         const int tn = t % ntn, tk = t / ntn; const int n0 = tn * 64, k0 = tk * 128;
;         if (t + G < total) prefetch(t + G);
.LBB0_218:
	s_mul_i32 s8, s15, 0x8200
	s_add_i32 s19, s8, 0
	v_add3_u32 v21, s19, v0, v27
	v_add_u32_e32 v28, 0x2080, v21
	s_waitcnt vmcnt(2)
	ds_write2_b32 v21, v4, v5 offset1:1
	ds_write2_b32 v21, v6, v7 offset0:2 offset1:3
	s_waitcnt vmcnt(2)
	ds_write2_b32 v28, v8, v9 offset1:1
	v_add_u32_e32 v28, 0x2088, v21
	ds_write2_b32 v28, v10, v11 offset1:1
	v_add_u32_e32 v28, 0x4100, v21
	s_waitcnt vmcnt(2)
	ds_write2_b32 v28, v12, v13 offset1:1
	v_add_u32_e32 v28, 0x4108, v21
	ds_write2_b32 v28, v14, v15 offset1:1
	v_add_u32_e32 v28, 0x6180, v21
	v_add_u32_e32 v21, 0x6188, v21
	s_waitcnt vmcnt(2)
	ds_write2_b32 v28, v16, v17 offset1:1
	ds_write2_b32 v21, v18, v19 offset1:1
	s_waitcnt lgkmcnt(0)
	s_barrier
	s_add_i32 s17, s20, s3
	s_cmpk_gt_i32 s17, 0x1ff
	s_cselect_b64 s[8:9], -1, 0
	s_cmpk_lt_i32 s17, 0x200
	s_mov_b64 s[12:13], -1
	s_cbranch_scc1 .LBB0_220
	s_add_i32 s18, s16, s14
	s_mov_b64 s[12:13], 0

; #define LAS __attribute__((address_space(3)))
; __device__ __forceinline__ void convert_weight(int wv, const float* __restrict__ src, int ldsrc, int Ksrc, bf16_t* dst, int ldd, int koff, int ntn, const float* kscale, int mode, LAS float* tile, int pidx, int pcnt) {
;     ...
;     int t = pidx; int buf = 0;
;     if (t < total) prefetch(t);
;     for (; t < total; t += G) {
;         LAS float* tl = tile + buf * (128 * 65);
; __device__ __forceinline__ void convert_layer(int wv, PP P, int L, int mask, LAS float* tile, int pidx, int pcnt) {
;     ...
;     if (mask & 8) convert_weight(wv, P->w_up + (size_t)L * D * NUP, NUP, D, (bf16_t*)(dob + DO_WUP), D, 0, NUP / 64, P->norm_ffn + L * D, 0, tile, pidx, pcnt);
.LBB0_540:
	s_load_dwordx2 s[14:15], s[12:13], 0x98
	v_lshlrev_b32_e32 v22, 4, v28
	v_and_b32_e32 v22, 0x70, v22
	v_ashrrev_i32_e32 v30, 3, v29
	v_mul_u32_u24_e32 v31, 0x104, v22
	s_waitcnt lgkmcnt(0)
	s_add_u32 s14, s14, 0x5200000
	s_addc_u32 s15, s15, 0
	v_mul_lo_u32 v32, v1, s87
	s_lshl_b32 s23, s20, 6
	s_lshl_b32 s21, s33, 6
	s_mov_b32 s22, 0
	v_lshlrev_b32_e32 v22, 1, v22
	s_mov_b32 s26, s20
	s_waitcnt vmcnt(0)
	s_branch .LBB0_542

; #define LAS __attribute__((address_space(3)))
; __device__ __forceinline__ void lds_barrier() { asm volatile("s_waitcnt lgkmcnt(0)" ::: "memory"); __builtin_amdgcn_s_barrier(); asm volatile("" ::: "memory"); }
; __device__ __forceinline__ void convert_weight(int wv, const float* __restrict__ src, int ldsrc, int Ksrc, bf16_t* dst, int ldd, int koff, int ntn, const float* kscale, int mode, LAS float* tile, int pidx, int pcnt) {
;     ...
;     for (; t < total; t += G) {
;         LAS float* tl = tile + buf * (128 * 65);
; #pragma unroll
;         for (int i = 0; i < 4; ++i) { const int kk = kk0 + i * 32;
;             tl[kk * 65 + n4 + 0] = v[i][0] * ks[i]; tl[kk * 65 + n4 + 1] = v[i][1] * ks[i]; tl[kk * 65 + n4 + 2] = v[i][2] * ks[i]; tl[kk * 65 + n4 + 3] = v[i][3] * ks[i]; }
;         lds_barrier();
;         const int tn = t % ntn, tk = t / ntn; const int n0 = tn * 64, k0 = tk * 128;
;         if (t + G < total) prefetch(t + G);
.LBB0_542:
	s_mul_i32 s16, s22, 0x8200
	s_add_i32 s27, s16, 0
	v_add3_u32 v23, s27, v2, v32
	s_waitcnt vmcnt(2)
	v_pk_mul_f32 v[28:29], v[4:5], v[20:21] op_sel_hi:[1,0]
	ds_write2_b32 v23, v28, v29 offset1:1
	v_pk_mul_f32 v[28:29], v[6:7], v[20:21] op_sel_hi:[1,0]
	ds_write2_b32 v23, v28, v29 offset0:2 offset1:3
	s_waitcnt vmcnt(2)
	v_pk_mul_f32 v[28:29], v[8:9], v[0:1] op_sel_hi:[1,0]
	v_add_u32_e32 v33, 0x2080, v23
	ds_write2_b32 v33, v28, v29 offset1:1
	v_pk_mul_f32 v[28:29], v[10:11], v[0:1] op_sel_hi:[1,0]
	v_add_u32_e32 v33, 0x2088, v23
	ds_write2_b32 v33, v28, v29 offset1:1
	s_waitcnt vmcnt(2)
	v_pk_mul_f32 v[28:29], v[12:13], v[26:27] op_sel_hi:[1,0]
	v_add_u32_e32 v33, 0x4100, v23
	ds_write2_b32 v33, v28, v29 offset1:1
	v_pk_mul_f32 v[28:29], v[14:15], v[26:27] op_sel_hi:[1,0]
	v_add_u32_e32 v33, 0x4108, v23
	ds_write2_b32 v33, v28, v29 offset1:1
	s_waitcnt vmcnt(2)
	v_pk_mul_f32 v[28:29], v[16:17], v[24:25] op_sel_hi:[1,0]
	v_add_u32_e32 v33, 0x6180, v23
	ds_write2_b32 v33, v28, v29 offset1:1
	v_pk_mul_f32 v[28:29], v[18:19], v[24:25] op_sel_hi:[1,0]
	v_add_u32_e32 v23, 0x6188, v23
	ds_write2_b32 v23, v28, v29 offset1:1
	s_waitcnt lgkmcnt(0)
	s_barrier
	s_add_i32 s24, s26, s33
	s_cmpk_gt_i32 s24, 0xaff
	s_cselect_b64 s[16:17], -1, 0
	s_cmpk_lt_i32 s24, 0xb00
	s_mov_b64 s[18:19], -1
	s_cbranch_scc1 .LBB0_544
	s_add_i32 s25, s23, s21
	s_mov_b64 s[18:19], 0

; __device__ __forceinline__ void convert_weight(int wv, const float* __restrict__ src, int ldsrc, int Ksrc, bf16_t* dst, int ldd, int koff, int ntn, const float* kscale, int mode, LAS float* tile, int pidx, int pcnt) {
;     ...
;     auto prefetch = [&](int t) {
;         const int tn = t % ntn, tk = t / ntn; const int n0 = tn * 64, k0 = tk * 128;
;         int scol = n0, nvalid = 64;
;         if (mode == 1) { if (n0 < 5632) scol = n0; else if (n0 < 13312) scol = n0 + 8; else if (n0 == 13312) { scol = 5632; nvalid = 8; } else { scol = 0; nvalid = 0; } }
; #pragma unroll
;         for (int i = 0; i < 4; ++i) { const int kk = kk0 + i * 32; v[i] = (f32x4){0.f, 0.f, 0.f, 0.f};
;             if (n4 < nvalid) v[i] = *(const f32x4*)(src + (size_t)(k0 + kk) * ldsrc + scol + n4);
;             ks[i] = kscale ? kscale[k0 + kk] : 1.0f; }
;     };
;     int t = pidx; int buf = 0;
;     if (t < total) prefetch(t);
; __device__ __forceinline__ void convert_layer(int wv, PP P, int L, int mask, LAS float* tile, int pidx, int pcnt) {
;     ...
;     if (mask & 16) convert_weight(wv, P->w_down + (size_t)L * DFF * D, D, DFF, (bf16_t*)(ws + WS_WDOWN), DFF, 0, D / 64, nullptr, 0, tile, pidx, pcnt);
.LBB0_554:
	s_mov_b32 s8, s95
	s_waitcnt vmcnt(0)
	v_mov_b32_e32 v0, v3
	s_cmpk_gt_i32 s20, 0x57f
	s_cbranch_scc1 .LBB0_561
	s_load_dwordx2 s[4:5], s[12:13], 0x88
	s_mul_i32 s56, s34, 0xb00000
	s_lshl_b64 s[10:11], s[56:57], 2
	v_mbcnt_lo_u32_b32 v0, -1, v0
	v_mbcnt_hi_u32_b32 v20, -1, v0
	s_waitcnt lgkmcnt(0)
	s_add_u32 s4, s4, s10
	s_addc_u32 s5, s5, s11
	s_add_u32 s6, s6, 0x26600000
	s_addc_u32 s7, s7, 0
	v_lshl_or_b32 v21, s8, 6, v20
	s_ashr_i32 s8, s20, 31
	s_lshr_b32 s8, s8, 27
	s_add_i32 s9, s20, s8
	v_ashrrev_i32_e32 v22, 4, v21
	s_and_b32 s8, s9, 0x3ffffe0
	s_lshl_b32 s9, s9, 2
	v_lshlrev_b32_e32 v0, 2, v20
	s_and_b32 s10, s9, 0xffffff80
	v_add_u32_e32 v23, 32, v22
	v_add_u32_e32 v24, 64, v22
	v_add_u32_e32 v25, 0x60, v22
	v_and_b32_e32 v2, 60, v0
	s_sub_i32 s8, s20, s8
	v_add_u32_e32 v0, s10, v22
	v_add_u32_e32 v6, s10, v23
	v_add_u32_e32 v12, s10, v24
	v_add_u32_e32 v14, s10, v25
	s_lshl_b32 s8, s8, 6
	v_ashrrev_i32_e32 v1, 31, v0
	v_ashrrev_i32_e32 v7, 31, v6
	v_ashrrev_i32_e32 v13, 31, v12
	v_ashrrev_i32_e32 v15, 31, v14
	s_ashr_i32 s9, s8, 31
	v_lshlrev_b64 v[0:1], 13, v[0:1]
	v_lshlrev_b64 v[6:7], 13, v[6:7]
	v_lshlrev_b64 v[12:13], 13, v[12:13]
	v_lshlrev_b64 v[14:15], 13, v[14:15]
	v_lshl_add_u64 v[0:1], s[4:5], 0, v[0:1]
	s_lshl_b64 s[8:9], s[8:9], 2
	v_lshl_add_u64 v[6:7], s[4:5], 0, v[6:7]
	v_lshl_add_u64 v[12:13], s[4:5], 0, v[12:13]
	v_lshl_add_u64 v[14:15], s[4:5], 0, v[14:15]
	v_lshl_add_u64 v[4:5], v[0:1], 0, s[8:9]
	v_lshlrev_b32_e32 v0, 2, v2
	v_mov_b32_e32 v1, v3
	v_lshl_add_u64 v[6:7], v[6:7], 0, s[8:9]
	v_lshl_add_u64 v[12:13], v[12:13], 0, s[8:9]
	v_lshl_add_u64 v[14:15], v[14:15], 0, s[8:9]
	v_lshl_add_u64 v[4:5], v[4:5], 0, v[0:1]
	v_lshl_add_u64 v[8:9], v[6:7], 0, v[0:1]
	v_lshl_add_u64 v[12:13], v[12:13], 0, v[0:1]
	v_lshl_add_u64 v[16:17], v[14:15], 0, v[0:1]
	global_load_dwordx4 v[4:7], v[4:5], off
	s_nop 0
	global_load_dwordx4 v[8:11], v[8:9], off
	s_nop 0
	global_load_dwordx4 v[12:15], v[12:13], off
	s_nop 0
	global_load_dwordx4 v[16:19], v[16:17], off
	v_lshlrev_b32_e32 v20, 4, v20
	v_and_b32_e32 v28, 0x70, v20
	v_ashrrev_i32_e32 v1, 3, v21
	v_mul_u32_u24_e32 v26, 0x104, v28
	v_mul_lo_u32 v27, v22, s87
	s_lshl_b32 s14, s20, 6
	s_lshl_b32 s12, s33, 6
	s_mov_b32 s13, 0
	v_lshlrev_b32_e32 v20, 2, v2
	v_lshlrev_b32_e32 v2, 1, v28
	s_waitcnt vmcnt(0)
	s_branch .LBB0_557

; #define LAS __attribute__((address_space(3)))
; __device__ __forceinline__ void lds_barrier() { asm volatile("s_waitcnt lgkmcnt(0)" ::: "memory"); __builtin_amdgcn_s_barrier(); asm volatile("" ::: "memory"); }
; __device__ __forceinline__ void convert_weight(int wv, const float* __restrict__ src, int ldsrc, int Ksrc, bf16_t* dst, int ldd, int koff, int ntn, const float* kscale, int mode, LAS float* tile, int pidx, int pcnt) {
;     ...
;     for (; t < total; t += G) {
;         LAS float* tl = tile + buf * (128 * 65);
; #pragma unroll
;         for (int i = 0; i < 4; ++i) { const int kk = kk0 + i * 32;
;             tl[kk * 65 + n4 + 0] = v[i][0] * ks[i]; tl[kk * 65 + n4 + 1] = v[i][1] * ks[i]; tl[kk * 65 + n4 + 2] = v[i][2] * ks[i]; tl[kk * 65 + n4 + 3] = v[i][3] * ks[i]; }
;         lds_barrier();
;         const int tn = t % ntn, tk = t / ntn; const int n0 = tn * 64, k0 = tk * 128;
;         if (t + G < total) prefetch(t + G);
.LBB0_557:
	s_mul_i32 s8, s13, 0x8200
	s_add_i32 s17, s8, 0
	v_add3_u32 v21, s17, v0, v27
	v_add_u32_e32 v28, 0x2080, v21
	s_waitcnt vmcnt(2)
	ds_write2_b32 v21, v4, v5 offset1:1
	ds_write2_b32 v21, v6, v7 offset0:2 offset1:3
	s_waitcnt vmcnt(2)
	ds_write2_b32 v28, v8, v9 offset1:1
	v_add_u32_e32 v28, 0x2088, v21
	ds_write2_b32 v28, v10, v11 offset1:1
	v_add_u32_e32 v28, 0x4100, v21
	s_waitcnt vmcnt(2)
	ds_write2_b32 v28, v12, v13 offset1:1
	v_add_u32_e32 v28, 0x4108, v21
	ds_write2_b32 v28, v14, v15 offset1:1
	v_add_u32_e32 v28, 0x6180, v21
	v_add_u32_e32 v21, 0x6188, v21
	s_waitcnt vmcnt(2)
	ds_write2_b32 v28, v16, v17 offset1:1
	ds_write2_b32 v21, v18, v19 offset1:1
	s_waitcnt lgkmcnt(0)
	s_barrier
	s_add_i32 s15, s20, s33
	s_cmpk_gt_i32 s15, 0x57f
	s_cselect_b64 s[8:9], -1, 0
	s_cmpk_lt_i32 s15, 0x580
	s_mov_b64 s[10:11], -1
	s_cbranch_scc1 .LBB0_559
	s_add_i32 s16, s14, s12
	s_mov_b64 s[10:11], 0

; #define LAS __attribute__((address_space(3)))
; __device__ __forceinline__ void convert_weight(int wv, const float* __restrict__ src, int ldsrc, int Ksrc, bf16_t* dst, int ldd, int koff, int ntn, const float* kscale, int mode, LAS float* tile, int pidx, int pcnt) {
;     ...
;     int t = pidx; int buf = 0;
;     if (t < total) prefetch(t);
;     for (; t < total; t += G) {
;         LAS float* tl = tile + buf * (128 * 65);
; __device__ __forceinline__ void convert_layer(int wv, PP P, int L, int mask, LAS float* tile, int pidx, int pcnt) {
;     ...
;     if (mask & 1) convert_weight(wv, P->w_in + (size_t)L * D * DIN, DIN, D, (bf16_t*)(ws + WS_WIN), D, 0, NZ / 64, P->norm_mix + L * D, 1, tile, pidx, pcnt);
.LBB0_671:
	v_lshlrev_b32_e32 v1, 4, v32
	s_waitcnt lgkmcnt(0)
	s_add_u32 s12, s6, 0x23100000
	v_and_b32_e32 v2, 0x70, v1
	s_addc_u32 s13, s7, 0
	v_cmp_gt_u32_e64 s[6:7], 8, v20
	v_ashrrev_i32_e32 v23, 3, v33
	v_mul_u32_u24_e32 v36, 0x104, v2
	v_mul_lo_u32 v37, v21, s87
	s_lshl_b32 s25, s22, 6
	s_lshl_b32 s23, s33, 6
	s_mov_b32 s24, 0
	v_lshlrev_b32_e32 v26, 1, v2
	s_waitcnt vmcnt(0)
	s_branch .LBB0_675

; #define LAS __attribute__((address_space(3)))
; __device__ __forceinline__ void lds_barrier() { asm volatile("s_waitcnt lgkmcnt(0)" ::: "memory"); __builtin_amdgcn_s_barrier(); asm volatile("" ::: "memory"); }
; __device__ __forceinline__ void convert_weight(int wv, const float* __restrict__ src, int ldsrc, int Ksrc, bf16_t* dst, int ldd, int koff, int ntn, const float* kscale, int mode, LAS float* tile, int pidx, int pcnt) {
;     ...
;     for (; t < total; t += G) {
;         LAS float* tl = tile + buf * (128 * 65);
; #pragma unroll
;         for (int i = 0; i < 4; ++i) { const int kk = kk0 + i * 32;
;             tl[kk * 65 + n4 + 0] = v[i][0] * ks[i]; tl[kk * 65 + n4 + 1] = v[i][1] * ks[i]; tl[kk * 65 + n4 + 2] = v[i][2] * ks[i]; tl[kk * 65 + n4 + 3] = v[i][3] * ks[i]; }
;         lds_barrier();
;         const int tn = t % ntn, tk = t / ntn; const int n0 = tn * 64, k0 = tk * 128;
;         if (t + G < total) prefetch(t + G);
.LBB0_675:
	s_mul_i32 s14, s24, 0x8200
	s_add_i32 s28, s14, 0
	v_add3_u32 v1, s28, v22, v37
	s_waitcnt vmcnt(2)
	v_pk_mul_f32 v[32:33], v[4:5], v[24:25] op_sel_hi:[1,0]
	ds_write2_b32 v1, v32, v33 offset1:1
	v_pk_mul_f32 v[32:33], v[6:7], v[24:25] op_sel_hi:[1,0]
	ds_write2_b32 v1, v32, v33 offset0:2 offset1:3
	v_pk_mul_f32 v[32:33], v[8:9], v[28:29] op_sel_hi:[1,0]
	v_add_u32_e32 v2, 0x2080, v1
	ds_write2_b32 v2, v32, v33 offset1:1
	v_pk_mul_f32 v[32:33], v[10:11], v[28:29] op_sel_hi:[1,0]
	v_add_u32_e32 v2, 0x2088, v1
	ds_write2_b32 v2, v32, v33 offset1:1
	v_pk_mul_f32 v[32:33], v[12:13], v[30:31] op_sel_hi:[1,0]
	v_add_u32_e32 v2, 0x4100, v1
	ds_write2_b32 v2, v32, v33 offset1:1
	v_pk_mul_f32 v[32:33], v[14:15], v[30:31] op_sel_hi:[1,0]
	v_add_u32_e32 v2, 0x4108, v1
	ds_write2_b32 v2, v32, v33 offset1:1
	v_pk_mul_f32 v[32:33], v[16:17], v[0:1] op_sel_hi:[1,0]
	v_add_u32_e32 v2, 0x6180, v1
	ds_write2_b32 v2, v32, v33 offset1:1
	v_pk_mul_f32 v[32:33], v[18:19], v[0:1] op_sel_hi:[1,0]
	v_add_u32_e32 v1, 0x6188, v1
	ds_write2_b32 v1, v32, v33 offset1:1
	s_waitcnt lgkmcnt(0)
	s_barrier
	s_add_i32 s26, s22, s33
	s_cmpk_gt_i32 s26, 0xd3f
	s_cselect_b64 s[14:15], -1, 0
	s_cmpk_lt_i32 s26, 0xd40
	s_mov_b64 s[16:17], -1
	s_cbranch_scc1 .LBB0_677
	s_add_i32 s27, s25, s23
	s_mov_b64 s[16:17], 0

; __device__ __forceinline__ void convert_weight(int wv, const float* __restrict__ src, int ldsrc, int Ksrc, bf16_t* dst, int ldd, int koff, int ntn, const float* kscale, int mode, LAS float* tile, int pidx, int pcnt) {
;     ...
;     auto prefetch = [&](int t) {
;         const int tn = t % ntn, tk = t / ntn; const int n0 = tn * 64, k0 = tk * 128;
;         int scol = n0, nvalid = 64;
;         if (mode == 1) { if (n0 < 5632) scol = n0; else if (n0 < 13312) scol = n0 + 8; else if (n0 == 13312) { scol = 5632; nvalid = 8; } else { scol = 0; nvalid = 0; } }
; #pragma unroll
;         for (int i = 0; i < 4; ++i) { const int kk = kk0 + i * 32; v[i] = (f32x4){0.f, 0.f, 0.f, 0.f};
;             if (n4 < nvalid) v[i] = *(const f32x4*)(src + (size_t)(k0 + kk) * ldsrc + scol + n4);
;             ks[i] = kscale ? kscale[k0 + kk] : 1.0f; }
;     };
;     int t = pidx; int buf = 0;
;     if (t < total) prefetch(t);
; __device__ __forceinline__ void convert_layer(int wv, PP P, int L, int mask, LAS float* tile, int pidx, int pcnt) {
;     ...
;         convert_weight(wv, P->w_br_a + (size_t)L * 512 * D, D, 512, wbr, D, 0, D / 64, nullptr, 0, tile, pidx, pcnt);
.LBB0_771:
	v_readlane_b32 s4, v254, 30
	v_readlane_b32 s5, v254, 31
	s_and_b64 vcc, exec, s[4:5]
	s_cbranch_vccnz .LBB0_802
	s_mov_b32 s4, s81
	v_readlane_b32 s5, v254, 7
	s_cmp_lt_i32 s4, s5
	v_readlane_b32 s8, v254, 5
	s_cselect_b64 s[6:7], -1, 0
	v_readlane_b32 s9, v254, 6
	s_or_b64 s[6:7], s[8:9], s[6:7]
	s_and_b64 vcc, exec, s[6:7]
	s_cbranch_vccnz .LBB0_802
	s_mov_b64 s[6:7], s[0:1]
	v_readlane_b32 s5, v254, 7
	s_sub_i32 s18, s4, s5
	s_load_dwordx2 s[4:5], s[6:7], 0x98
	s_cmpk_lt_i32 s18, 0x80
	s_mov_b32 s14, s95
	v_mov_b32_e32 v0, v3
	s_cselect_b64 s[8:9], -1, 0
	s_cmpk_gt_i32 s18, 0x7f
	s_cbranch_scc1 .LBB0_780
	s_load_dwordx2 s[12:13], s[6:7], 0x48
	s_waitcnt lgkmcnt(0)
	s_add_u32 s10, s4, 0x4200000
	v_mbcnt_lo_u32_b32 v0, -1, v0
	s_addc_u32 s11, s5, 0
	v_mbcnt_hi_u32_b32 v20, -1, v0
	s_add_u32 s12, s12, 0x400000
	v_lshl_or_b32 v21, s14, 6, v20
	s_sext_i32_i16 s14, s18
	s_addc_u32 s13, s13, 0
	s_bfe_u32 s14, s14, 0x5001a
	s_add_i32 s14, s18, s14
	s_sext_i32_i16 s15, s14
	v_ashrrev_i32_e32 v22, 4, v21
	s_and_b32 s14, s14, 0xffe0
	s_lshl_b32 s15, s15, 2
	v_lshlrev_b32_e32 v0, 2, v20
	s_sub_i32 s14, s18, s14
	s_and_b32 s16, s15, 0xffffff80
	v_add_u32_e32 v23, 32, v22
	v_add_u32_e32 v24, 64, v22
	v_add_u32_e32 v25, 0x60, v22
	v_and_b32_e32 v2, 60, v0
	s_sext_i32_i16 s14, s14
	v_add_u32_e32 v0, s16, v22
	v_add_u32_e32 v6, s16, v23
	v_add_u32_e32 v12, s16, v24
	v_add_u32_e32 v14, s16, v25
	s_lshl_b32 s14, s14, 6
	v_ashrrev_i32_e32 v1, 31, v0
	v_ashrrev_i32_e32 v7, 31, v6
	v_ashrrev_i32_e32 v13, 31, v12
	v_ashrrev_i32_e32 v15, 31, v14
	s_ashr_i32 s15, s14, 31
	v_lshlrev_b64 v[0:1], 13, v[0:1]
	v_lshlrev_b64 v[6:7], 13, v[6:7]
	v_lshlrev_b64 v[12:13], 13, v[12:13]
	v_lshlrev_b64 v[14:15], 13, v[14:15]
	v_lshl_add_u64 v[0:1], s[12:13], 0, v[0:1]
	s_lshl_b64 s[14:15], s[14:15], 2
	v_lshl_add_u64 v[6:7], s[12:13], 0, v[6:7]
	v_lshl_add_u64 v[12:13], s[12:13], 0, v[12:13]
	v_lshl_add_u64 v[14:15], s[12:13], 0, v[14:15]
	v_lshl_add_u64 v[4:5], v[0:1], 0, s[14:15]
	v_lshlrev_b32_e32 v0, 2, v2
	v_mov_b32_e32 v1, v3
	v_lshl_add_u64 v[6:7], v[6:7], 0, s[14:15]
	v_lshl_add_u64 v[12:13], v[12:13], 0, s[14:15]
	v_lshl_add_u64 v[14:15], v[14:15], 0, s[14:15]
	v_lshl_add_u64 v[4:5], v[4:5], 0, v[0:1]
	v_lshl_add_u64 v[8:9], v[6:7], 0, v[0:1]
	v_lshl_add_u64 v[12:13], v[12:13], 0, v[0:1]
	v_lshl_add_u64 v[16:17], v[14:15], 0, v[0:1]
	global_load_dwordx4 v[4:7], v[4:5], off
	s_nop 0
	global_load_dwordx4 v[8:11], v[8:9], off
	s_nop 0
	global_load_dwordx4 v[12:15], v[12:13], off
	s_nop 0
	global_load_dwordx4 v[16:19], v[16:17], off
	v_lshlrev_b32_e32 v20, 4, v20
	v_and_b32_e32 v28, 0x70, v20
	v_readlane_b32 s14, v254, 8
	v_ashrrev_i32_e32 v1, 3, v21
	v_mul_u32_u24_e32 v26, 0x104, v28
	v_mul_lo_u32 v27, v22, s87
	s_lshl_b32 s21, s18, 6
	s_lshl_b32 s19, s14, 6
	s_mov_b32 s20, 0
	v_lshlrev_b32_e32 v20, 2, v2
	v_lshlrev_b32_e32 v2, 1, v28
	s_mov_b32 s24, s18
	s_waitcnt vmcnt(0)
	s_branch .LBB0_776

; #define LAS __attribute__((address_space(3)))
; __device__ __forceinline__ void lds_barrier() { asm volatile("s_waitcnt lgkmcnt(0)" ::: "memory"); __builtin_amdgcn_s_barrier(); asm volatile("" ::: "memory"); }
; __device__ __forceinline__ void convert_weight(int wv, const float* __restrict__ src, int ldsrc, int Ksrc, bf16_t* dst, int ldd, int koff, int ntn, const float* kscale, int mode, LAS float* tile, int pidx, int pcnt) {
;     ...
;     for (; t < total; t += G) {
;         LAS float* tl = tile + buf * (128 * 65);
; #pragma unroll
;         for (int i = 0; i < 4; ++i) { const int kk = kk0 + i * 32;
;             tl[kk * 65 + n4 + 0] = v[i][0] * ks[i]; tl[kk * 65 + n4 + 1] = v[i][1] * ks[i]; tl[kk * 65 + n4 + 2] = v[i][2] * ks[i]; tl[kk * 65 + n4 + 3] = v[i][3] * ks[i]; }
;         lds_barrier();
;         const int tn = t % ntn, tk = t / ntn; const int n0 = tn * 64, k0 = tk * 128;
;         if (t + G < total) prefetch(t + G);
.LBB0_776:
	s_mul_i32 s14, s20, 0x8200
	s_add_i32 s25, s14, 0
	v_add3_u32 v21, s25, v0, v27
	v_add_u32_e32 v28, 0x2080, v21
	s_waitcnt vmcnt(2)
	ds_write2_b32 v21, v4, v5 offset1:1
	ds_write2_b32 v21, v6, v7 offset0:2 offset1:3
	ds_write2_b32 v28, v8, v9 offset1:1
	v_add_u32_e32 v28, 0x2088, v21
	ds_write2_b32 v28, v10, v11 offset1:1
	v_add_u32_e32 v28, 0x4100, v21
	ds_write2_b32 v28, v12, v13 offset1:1
	v_add_u32_e32 v28, 0x4108, v21
	ds_write2_b32 v28, v14, v15 offset1:1
	v_add_u32_e32 v28, 0x6180, v21
	v_add_u32_e32 v21, 0x6188, v21
	ds_write2_b32 v28, v16, v17 offset1:1
	ds_write2_b32 v21, v18, v19 offset1:1
	v_readlane_b32 s14, v254, 8
	s_waitcnt lgkmcnt(0)
	s_barrier
	s_add_i32 s22, s24, s14
	s_cmpk_gt_i32 s22, 0x7f
	s_cselect_b64 s[14:15], -1, 0
	s_cmpk_lt_i32 s22, 0x80
	s_mov_b64 s[16:17], -1
	s_cbranch_scc1 .LBB0_778
	s_add_i32 s23, s21, s19
	s_mov_b64 s[16:17], 0

; __device__ __forceinline__ void convert_weight(int wv, const float* __restrict__ src, int ldsrc, int Ksrc, bf16_t* dst, int ldd, int koff, int ntn, const float* kscale, int mode, LAS float* tile, int pidx, int pcnt) {
;     ...
;     auto prefetch = [&](int t) {
;         const int tn = t % ntn, tk = t / ntn; const int n0 = tn * 64, k0 = tk * 128;
;         int scol = n0, nvalid = 64;
;         if (mode == 1) { if (n0 < 5632) scol = n0; else if (n0 < 13312) scol = n0 + 8; else if (n0 == 13312) { scol = 5632; nvalid = 8; } else { scol = 0; nvalid = 0; } }
; #pragma unroll
;         for (int i = 0; i < 4; ++i) { const int kk = kk0 + i * 32; v[i] = (f32x4){0.f, 0.f, 0.f, 0.f};
;             if (n4 < nvalid) v[i] = *(const f32x4*)(src + (size_t)(k0 + kk) * ldsrc + scol + n4);
;             ks[i] = kscale ? kscale[k0 + kk] : 1.0f; }
;     };
;     int t = pidx; int buf = 0;
;     if (t < total) prefetch(t);
; __device__ __forceinline__ void convert_layer(int wv, PP P, int L, int mask, LAS float* tile, int pidx, int pcnt) {
;     ...
;         convert_weight(wv, P->w_br_m + (size_t)L * 1024 * D, D, 1024, wbr, D, 512, D / 64, nullptr, 0, tile, pidx, pcnt);
.LBB0_780:
	s_mov_b32 s10, s95
	v_mov_b32_e32 v0, v3
	s_cmpk_gt_i32 s18, 0xff
	s_waitcnt vmcnt(0) lgkmcnt(0)
	s_barrier
	s_cbranch_scc1 .LBB0_787
	s_load_dwordx2 s[12:13], s[6:7], 0x50
	v_mbcnt_lo_u32_b32 v0, -1, v0
	v_mbcnt_hi_u32_b32 v20, -1, v0
	v_lshl_or_b32 v21, s10, 6, v20
	v_ashrrev_i32_e32 v22, 4, v21
	s_waitcnt lgkmcnt(0)
	s_add_u32 s10, s12, 0x800000
	s_addc_u32 s11, s13, 0
	s_ashr_i32 s12, s18, 31
	s_lshr_b32 s12, s12, 27
	s_add_i32 s13, s18, s12
	s_and_b32 s12, s13, 0x3ffffe0
	s_lshl_b32 s13, s13, 2
	v_lshlrev_b32_e32 v0, 2, v20
	s_and_b32 s14, s13, 0xffffff80
	v_add_u32_e32 v23, 32, v22
	v_add_u32_e32 v24, 64, v22
	v_add_u32_e32 v25, 0x60, v22
	v_and_b32_e32 v2, 60, v0
	s_sub_i32 s12, s18, s12
	v_add_u32_e32 v0, s14, v22
	v_add_u32_e32 v6, s14, v23
	v_add_u32_e32 v12, s14, v24
	v_add_u32_e32 v14, s14, v25
	s_lshl_b32 s12, s12, 6
	v_ashrrev_i32_e32 v1, 31, v0
	v_ashrrev_i32_e32 v7, 31, v6
	v_ashrrev_i32_e32 v13, 31, v12
	v_ashrrev_i32_e32 v15, 31, v14
	s_ashr_i32 s13, s12, 31
	v_lshlrev_b64 v[0:1], 13, v[0:1]
	v_lshlrev_b64 v[6:7], 13, v[6:7]
	v_lshlrev_b64 v[12:13], 13, v[12:13]
	v_lshlrev_b64 v[14:15], 13, v[14:15]
	v_lshl_add_u64 v[0:1], s[10:11], 0, v[0:1]
	s_lshl_b64 s[12:13], s[12:13], 2
	v_lshl_add_u64 v[6:7], s[10:11], 0, v[6:7]
	v_lshl_add_u64 v[12:13], s[10:11], 0, v[12:13]
	v_lshl_add_u64 v[14:15], s[10:11], 0, v[14:15]
	v_lshl_add_u64 v[4:5], v[0:1], 0, s[12:13]
	v_lshlrev_b32_e32 v0, 2, v2
	v_mov_b32_e32 v1, v3
	v_lshl_add_u64 v[6:7], v[6:7], 0, s[12:13]
	v_lshl_add_u64 v[12:13], v[12:13], 0, s[12:13]
	v_lshl_add_u64 v[14:15], v[14:15], 0, s[12:13]
	v_lshl_add_u64 v[4:5], v[4:5], 0, v[0:1]
	v_lshl_add_u64 v[8:9], v[6:7], 0, v[0:1]
	v_lshl_add_u64 v[12:13], v[12:13], 0, v[0:1]
	v_lshl_add_u64 v[16:17], v[14:15], 0, v[0:1]
	global_load_dwordx4 v[4:7], v[4:5], off
	s_nop 0
	global_load_dwordx4 v[8:11], v[8:9], off
	s_nop 0
	global_load_dwordx4 v[12:15], v[12:13], off
	s_nop 0
	global_load_dwordx4 v[16:19], v[16:17], off
	v_lshlrev_b32_e32 v20, 4, v20
	v_and_b32_e32 v28, 0x70, v20
	s_add_u32 s12, s4, 0x4200400
	v_readlane_b32 s14, v254, 8
	v_ashrrev_i32_e32 v1, 3, v21
	v_mul_u32_u24_e32 v26, 0x104, v28
	s_addc_u32 s13, s5, 0
	v_mul_lo_u32 v27, v22, s87
	s_lshl_b32 s21, s18, 6
	s_lshl_b32 s19, s14, 6
	s_mov_b32 s20, 0
	v_lshlrev_b32_e32 v20, 2, v2
	v_lshlrev_b32_e32 v2, 1, v28
	s_mov_b32 s24, s18
	s_waitcnt vmcnt(0)
	s_branch .LBB0_783

; #define LAS __attribute__((address_space(3)))
; __device__ __forceinline__ void lds_barrier() { asm volatile("s_waitcnt lgkmcnt(0)" ::: "memory"); __builtin_amdgcn_s_barrier(); asm volatile("" ::: "memory"); }
; __device__ __forceinline__ void convert_weight(int wv, const float* __restrict__ src, int ldsrc, int Ksrc, bf16_t* dst, int ldd, int koff, int ntn, const float* kscale, int mode, LAS float* tile, int pidx, int pcnt) {
;     ...
;     for (; t < total; t += G) {
;         LAS float* tl = tile + buf * (128 * 65);
; #pragma unroll
;         for (int i = 0; i < 4; ++i) { const int kk = kk0 + i * 32;
;             tl[kk * 65 + n4 + 0] = v[i][0] * ks[i]; tl[kk * 65 + n4 + 1] = v[i][1] * ks[i]; tl[kk * 65 + n4 + 2] = v[i][2] * ks[i]; tl[kk * 65 + n4 + 3] = v[i][3] * ks[i]; }
;         lds_barrier();
;         const int tn = t % ntn, tk = t / ntn; const int n0 = tn * 64, k0 = tk * 128;
;         if (t + G < total) prefetch(t + G);
.LBB0_783:
	s_mul_i32 s14, s20, 0x8200
	s_add_i32 s25, s14, 0
	v_add3_u32 v21, s25, v0, v27
	v_add_u32_e32 v28, 0x2080, v21
	s_waitcnt vmcnt(2)
	ds_write2_b32 v21, v4, v5 offset1:1
	ds_write2_b32 v21, v6, v7 offset0:2 offset1:3
	s_waitcnt vmcnt(2)
	ds_write2_b32 v28, v8, v9 offset1:1
	v_add_u32_e32 v28, 0x2088, v21
	ds_write2_b32 v28, v10, v11 offset1:1
	v_add_u32_e32 v28, 0x4100, v21
	s_waitcnt vmcnt(2)
	ds_write2_b32 v28, v12, v13 offset1:1
	v_add_u32_e32 v28, 0x4108, v21
	ds_write2_b32 v28, v14, v15 offset1:1
	v_add_u32_e32 v28, 0x6180, v21
	v_add_u32_e32 v21, 0x6188, v21
	s_waitcnt vmcnt(2)
	ds_write2_b32 v28, v16, v17 offset1:1
	ds_write2_b32 v21, v18, v19 offset1:1
	v_readlane_b32 s14, v254, 8
	s_waitcnt lgkmcnt(0)
	s_barrier
	s_add_i32 s22, s24, s14
	s_cmpk_gt_i32 s22, 0xff
	s_cselect_b64 s[14:15], -1, 0
	s_cmpk_lt_i32 s22, 0x100
	s_mov_b64 s[16:17], -1
	s_cbranch_scc1 .LBB0_785
	s_add_i32 s23, s21, s19
	s_mov_b64 s[16:17], 0

; __device__ __forceinline__ void convert_weight(int wv, const float* __restrict__ src, int ldsrc, int Ksrc, bf16_t* dst, int ldd, int koff, int ntn, const float* kscale, int mode, LAS float* tile, int pidx, int pcnt) {
;     ...
;     auto prefetch = [&](int t) {
;         const int tn = t % ntn, tk = t / ntn; const int n0 = tn * 64, k0 = tk * 128;
;         int scol = n0, nvalid = 64;
;         if (mode == 1) { if (n0 < 5632) scol = n0; else if (n0 < 13312) scol = n0 + 8; else if (n0 == 13312) { scol = 5632; nvalid = 8; } else { scol = 0; nvalid = 0; } }
; #pragma unroll
;         for (int i = 0; i < 4; ++i) { const int kk = kk0 + i * 32; v[i] = (f32x4){0.f, 0.f, 0.f, 0.f};
;             if (n4 < nvalid) v[i] = *(const f32x4*)(src + (size_t)(k0 + kk) * ldsrc + scol + n4);
;             ks[i] = kscale ? kscale[k0 + kk] : 1.0f; }
;     };
;     int t = pidx; int buf = 0;
;     if (t < total) prefetch(t);
; __device__ __forceinline__ void convert_layer(int wv, PP P, int L, int mask, LAS float* tile, int pidx, int pcnt) {
;     ...
;         convert_weight(wv, P->w_br_d + (size_t)L * 512 * D, D, 512, wbr, D, 1536, D / 64, nullptr, 0, tile, pidx, pcnt);
.LBB0_787:
	s_mov_b32 s10, s95
	v_mov_b32_e32 v0, v3
	s_andn2_b64 vcc, exec, s[8:9]
	s_barrier
	s_cbranch_vccnz .LBB0_794
	s_load_dwordx2 s[8:9], s[6:7], 0x58
	v_mbcnt_lo_u32_b32 v0, -1, v0
	v_mbcnt_hi_u32_b32 v20, -1, v0
	v_lshl_or_b32 v21, s10, 6, v20
	v_ashrrev_i32_e32 v22, 4, v21
	s_waitcnt lgkmcnt(0)
	s_add_u32 s8, s8, 0x400000
	s_addc_u32 s9, s9, 0
	s_ashr_i32 s10, s18, 31
	s_lshr_b32 s10, s10, 27
	s_add_i32 s11, s18, s10
	s_and_b32 s10, s11, 0x3ffffe0
	s_lshl_b32 s11, s11, 2
	v_lshlrev_b32_e32 v0, 2, v20
	s_and_b32 s12, s11, 0xffffff80
	v_add_u32_e32 v23, 32, v22
	v_add_u32_e32 v24, 64, v22
	v_add_u32_e32 v25, 0x60, v22
	v_and_b32_e32 v2, 60, v0
	s_sub_i32 s10, s18, s10
	v_add_u32_e32 v0, s12, v22
	s_waitcnt vmcnt(5)
	v_add_u32_e32 v6, s12, v23
	s_waitcnt vmcnt(3)
	v_add_u32_e32 v12, s12, v24
	v_add_u32_e32 v14, s12, v25
	s_lshl_b32 s10, s10, 6
	v_ashrrev_i32_e32 v1, 31, v0
	v_ashrrev_i32_e32 v7, 31, v6
	v_ashrrev_i32_e32 v13, 31, v12
	v_ashrrev_i32_e32 v15, 31, v14
	s_ashr_i32 s11, s10, 31
	v_lshlrev_b64 v[0:1], 13, v[0:1]
	v_lshlrev_b64 v[6:7], 13, v[6:7]
	v_lshlrev_b64 v[12:13], 13, v[12:13]
	v_lshlrev_b64 v[14:15], 13, v[14:15]
	v_lshl_add_u64 v[0:1], s[8:9], 0, v[0:1]
	s_lshl_b64 s[10:11], s[10:11], 2
	v_lshl_add_u64 v[6:7], s[8:9], 0, v[6:7]
	v_lshl_add_u64 v[12:13], s[8:9], 0, v[12:13]
	v_lshl_add_u64 v[14:15], s[8:9], 0, v[14:15]
	v_lshl_add_u64 v[4:5], v[0:1], 0, s[10:11]
	v_lshlrev_b32_e32 v0, 2, v2
	v_mov_b32_e32 v1, v3
	v_lshl_add_u64 v[6:7], v[6:7], 0, s[10:11]
	v_lshl_add_u64 v[12:13], v[12:13], 0, s[10:11]
	v_lshl_add_u64 v[14:15], v[14:15], 0, s[10:11]
	v_lshl_add_u64 v[4:5], v[4:5], 0, v[0:1]
	v_lshl_add_u64 v[8:9], v[6:7], 0, v[0:1]
	v_lshl_add_u64 v[12:13], v[12:13], 0, v[0:1]
	s_waitcnt vmcnt(2)
	v_lshl_add_u64 v[16:17], v[14:15], 0, v[0:1]
	global_load_dwordx4 v[4:7], v[4:5], off
	s_nop 0
	global_load_dwordx4 v[8:11], v[8:9], off
	s_nop 0
	global_load_dwordx4 v[12:15], v[12:13], off
	s_nop 0
	global_load_dwordx4 v[16:19], v[16:17], off
	v_lshlrev_b32_e32 v20, 4, v20
	v_and_b32_e32 v28, 0x70, v20
	s_add_u32 s10, s4, 0x4200c00
	v_readlane_b32 s12, v254, 8
	v_ashrrev_i32_e32 v1, 3, v21
	v_mul_u32_u24_e32 v26, 0x104, v28
	s_addc_u32 s11, s5, 0
	v_mul_lo_u32 v27, v22, s87
	s_lshl_b32 s19, s18, 6
	s_lshl_b32 s16, s12, 6
	s_mov_b32 s17, 0
	v_lshlrev_b32_e32 v20, 2, v2
	v_lshlrev_b32_e32 v2, 1, v28
	s_mov_b32 s22, s18
	s_waitcnt vmcnt(0)
	s_branch .LBB0_790

; #define LAS __attribute__((address_space(3)))
; __device__ __forceinline__ void lds_barrier() { asm volatile("s_waitcnt lgkmcnt(0)" ::: "memory"); __builtin_amdgcn_s_barrier(); asm volatile("" ::: "memory"); }
; __device__ __forceinline__ void convert_weight(int wv, const float* __restrict__ src, int ldsrc, int Ksrc, bf16_t* dst, int ldd, int koff, int ntn, const float* kscale, int mode, LAS float* tile, int pidx, int pcnt) {
;     ...
;     for (; t < total; t += G) {
;         LAS float* tl = tile + buf * (128 * 65);
; #pragma unroll
;         for (int i = 0; i < 4; ++i) { const int kk = kk0 + i * 32;
;             tl[kk * 65 + n4 + 0] = v[i][0] * ks[i]; tl[kk * 65 + n4 + 1] = v[i][1] * ks[i]; tl[kk * 65 + n4 + 2] = v[i][2] * ks[i]; tl[kk * 65 + n4 + 3] = v[i][3] * ks[i]; }
;         lds_barrier();
;         const int tn = t % ntn, tk = t / ntn; const int n0 = tn * 64, k0 = tk * 128;
;         if (t + G < total) prefetch(t + G);
.LBB0_790:
	s_mul_i32 s12, s17, 0x8200
	s_add_i32 s23, s12, 0
	v_add3_u32 v21, s23, v0, v27
	v_add_u32_e32 v28, 0x2080, v21
	s_waitcnt vmcnt(2)
	ds_write2_b32 v21, v4, v5 offset1:1
	ds_write2_b32 v21, v6, v7 offset0:2 offset1:3
	s_waitcnt vmcnt(2)
	ds_write2_b32 v28, v8, v9 offset1:1
	v_add_u32_e32 v28, 0x2088, v21
	ds_write2_b32 v28, v10, v11 offset1:1
	v_add_u32_e32 v28, 0x4100, v21
	s_waitcnt vmcnt(2)
	ds_write2_b32 v28, v12, v13 offset1:1
	v_add_u32_e32 v28, 0x4108, v21
	ds_write2_b32 v28, v14, v15 offset1:1
	v_add_u32_e32 v28, 0x6180, v21
	v_add_u32_e32 v21, 0x6188, v21
	s_waitcnt vmcnt(2)
	ds_write2_b32 v28, v16, v17 offset1:1
	ds_write2_b32 v21, v18, v19 offset1:1
	v_readlane_b32 s12, v254, 8
	s_waitcnt lgkmcnt(0)
	s_barrier
	s_add_i32 s20, s22, s12
	s_cmpk_gt_i32 s20, 0x7f
	s_cselect_b64 s[12:13], -1, 0
	s_cmpk_lt_i32 s20, 0x80
	s_mov_b64 s[14:15], -1
	s_cbranch_scc1 .LBB0_792
	s_add_i32 s21, s19, s16
	s_mov_b64 s[14:15], 0

; __device__ __forceinline__ void convert_weight(int wv, const float* __restrict__ src, int ldsrc, int Ksrc, bf16_t* dst, int ldd, int koff, int ntn, const float* kscale, int mode, LAS float* tile, int pidx, int pcnt) {
;     ...
;     auto prefetch = [&](int t) {
;         const int tn = t % ntn, tk = t / ntn; const int n0 = tn * 64, k0 = tk * 128;
;         int scol = n0, nvalid = 64;
;         if (mode == 1) { if (n0 < 5632) scol = n0; else if (n0 < 13312) scol = n0 + 8; else if (n0 == 13312) { scol = 5632; nvalid = 8; } else { scol = 0; nvalid = 0; } }
; #pragma unroll
;         for (int i = 0; i < 4; ++i) { const int kk = kk0 + i * 32; v[i] = (f32x4){0.f, 0.f, 0.f, 0.f};
;             if (n4 < nvalid) v[i] = *(const f32x4*)(src + (size_t)(k0 + kk) * ldsrc + scol + n4);
;             ks[i] = kscale ? kscale[k0 + kk] : 1.0f; }
;     };
;     int t = pidx; int buf = 0;
;     if (t < total) prefetch(t);
; __device__ __forceinline__ void convert_layer(int wv, PP P, int L, int mask, LAS float* tile, int pidx, int pcnt) {
;     ...
;     if (mask & 4) convert_weight(wv, P->w_out + (size_t)L * D * D, D, D, (bf16_t*)(dob + DO_WOUT), D, 0, D / 64, nullptr, 0, tile, pidx, pcnt);
.LBB0_794:
	s_mov_b32 s8, s95
	v_mov_b32_e32 v0, v3
	s_cmpk_gt_i32 s18, 0x1ff
	s_barrier
	s_cbranch_scc1 .LBB0_801
	s_load_dwordx2 s[6:7], s[6:7], 0x60
	v_mbcnt_lo_u32_b32 v0, -1, v0
	v_mbcnt_hi_u32_b32 v20, -1, v0
	v_lshl_or_b32 v21, s8, 6, v20
	v_ashrrev_i32_e32 v22, 4, v21
	s_waitcnt lgkmcnt(0)
	s_add_u32 s6, s6, 0x1000000
	s_addc_u32 s7, s7, 0
	s_add_u32 s4, s4, 0x4a00000
	s_addc_u32 s5, s5, 0
	s_ashr_i32 s8, s18, 31
	s_lshr_b32 s8, s8, 27
	s_add_i32 s9, s18, s8
	s_and_b32 s8, s9, 0x3ffffe0
	s_lshl_b32 s9, s9, 2
	v_lshlrev_b32_e32 v0, 2, v20
	s_and_b32 s10, s9, 0xffffff80
	v_add_u32_e32 v23, 32, v22
	v_add_u32_e32 v24, 64, v22
	v_add_u32_e32 v25, 0x60, v22
	v_and_b32_e32 v2, 60, v0
	s_sub_i32 s8, s18, s8
	v_add_u32_e32 v0, s10, v22
	s_waitcnt vmcnt(5)
	v_add_u32_e32 v6, s10, v23
	s_waitcnt vmcnt(3)
	v_add_u32_e32 v12, s10, v24
	v_add_u32_e32 v14, s10, v25
	s_lshl_b32 s8, s8, 6
	v_ashrrev_i32_e32 v1, 31, v0
	v_ashrrev_i32_e32 v7, 31, v6
	v_ashrrev_i32_e32 v13, 31, v12
	v_ashrrev_i32_e32 v15, 31, v14
	s_ashr_i32 s9, s8, 31
	v_lshlrev_b64 v[0:1], 13, v[0:1]
	v_lshlrev_b64 v[6:7], 13, v[6:7]
	v_lshlrev_b64 v[12:13], 13, v[12:13]
	v_lshlrev_b64 v[14:15], 13, v[14:15]
	v_lshl_add_u64 v[0:1], s[6:7], 0, v[0:1]
	s_lshl_b64 s[8:9], s[8:9], 2
	v_lshl_add_u64 v[6:7], s[6:7], 0, v[6:7]
	v_lshl_add_u64 v[12:13], s[6:7], 0, v[12:13]
	v_lshl_add_u64 v[14:15], s[6:7], 0, v[14:15]
	v_lshl_add_u64 v[4:5], v[0:1], 0, s[8:9]
	v_lshlrev_b32_e32 v0, 2, v2
	v_mov_b32_e32 v1, v3
	v_lshl_add_u64 v[6:7], v[6:7], 0, s[8:9]
	v_lshl_add_u64 v[12:13], v[12:13], 0, s[8:9]
	v_lshl_add_u64 v[14:15], v[14:15], 0, s[8:9]
	v_lshl_add_u64 v[4:5], v[4:5], 0, v[0:1]
	v_lshl_add_u64 v[8:9], v[6:7], 0, v[0:1]
	v_lshl_add_u64 v[12:13], v[12:13], 0, v[0:1]
	s_waitcnt vmcnt(2)
	v_lshl_add_u64 v[16:17], v[14:15], 0, v[0:1]
	global_load_dwordx4 v[4:7], v[4:5], off
	s_nop 0
	global_load_dwordx4 v[8:11], v[8:9], off
	s_nop 0
	global_load_dwordx4 v[12:15], v[12:13], off
	s_nop 0
	global_load_dwordx4 v[16:19], v[16:17], off
	v_lshlrev_b32_e32 v20, 4, v20
	v_and_b32_e32 v28, 0x70, v20
	v_readlane_b32 s8, v254, 8
	v_ashrrev_i32_e32 v1, 3, v21
	v_mul_u32_u24_e32 v26, 0x104, v28
	v_mul_lo_u32 v27, v22, s87
	s_lshl_b32 s14, s18, 6
	s_lshl_b32 s12, s8, 6
	s_mov_b32 s13, 0
	v_lshlrev_b32_e32 v20, 2, v2
	v_lshlrev_b32_e32 v2, 1, v28
	s_waitcnt vmcnt(0)
	s_branch .LBB0_797

; #define LAS __attribute__((address_space(3)))
; __device__ __forceinline__ void lds_barrier() { asm volatile("s_waitcnt lgkmcnt(0)" ::: "memory"); __builtin_amdgcn_s_barrier(); asm volatile("" ::: "memory"); }
; __device__ __forceinline__ void convert_weight(int wv, const float* __restrict__ src, int ldsrc, int Ksrc, bf16_t* dst, int ldd, int koff, int ntn, const float* kscale, int mode, LAS float* tile, int pidx, int pcnt) {
;     ...
;     for (; t < total; t += G) {
;         LAS float* tl = tile + buf * (128 * 65);
; #pragma unroll
;         for (int i = 0; i < 4; ++i) { const int kk = kk0 + i * 32;
;             tl[kk * 65 + n4 + 0] = v[i][0] * ks[i]; tl[kk * 65 + n4 + 1] = v[i][1] * ks[i]; tl[kk * 65 + n4 + 2] = v[i][2] * ks[i]; tl[kk * 65 + n4 + 3] = v[i][3] * ks[i]; }
;         lds_barrier();
;         const int tn = t % ntn, tk = t / ntn; const int n0 = tn * 64, k0 = tk * 128;
;         if (t + G < total) prefetch(t + G);
.LBB0_797:
	s_mul_i32 s8, s13, 0x8200
	s_add_i32 s17, s8, 0
	v_add3_u32 v21, s17, v0, v27
	v_add_u32_e32 v28, 0x2080, v21
	s_waitcnt vmcnt(2)
	ds_write2_b32 v21, v4, v5 offset1:1
	ds_write2_b32 v21, v6, v7 offset0:2 offset1:3
	s_waitcnt vmcnt(2)
	ds_write2_b32 v28, v8, v9 offset1:1
	v_add_u32_e32 v28, 0x2088, v21
	ds_write2_b32 v28, v10, v11 offset1:1
	v_add_u32_e32 v28, 0x4100, v21
	s_waitcnt vmcnt(2)
	ds_write2_b32 v28, v12, v13 offset1:1
	v_add_u32_e32 v28, 0x4108, v21
	ds_write2_b32 v28, v14, v15 offset1:1
	v_add_u32_e32 v28, 0x6180, v21
	v_add_u32_e32 v21, 0x6188, v21
	s_waitcnt vmcnt(2)
	ds_write2_b32 v28, v16, v17 offset1:1
	ds_write2_b32 v21, v18, v19 offset1:1
	v_readlane_b32 s8, v254, 8
	s_waitcnt lgkmcnt(0)
	s_barrier
	s_add_i32 s15, s18, s8
	s_cmpk_gt_i32 s15, 0x1ff
	s_cselect_b64 s[8:9], -1, 0
	s_cmpk_lt_i32 s15, 0x200
	s_mov_b64 s[10:11], -1
	s_cbranch_scc1 .LBB0_799
	s_add_i32 s16, s14, s12
	s_mov_b64 s[10:11], 0

; #define LAS __attribute__((address_space(3)))
; __device__ __forceinline__ void convert_weight(int wv, const float* __restrict__ src, int ldsrc, int Ksrc, bf16_t* dst, int ldd, int koff, int ntn, const float* kscale, int mode, LAS float* tile, int pidx, int pcnt) {
;     ...
;     int t = pidx; int buf = 0;
;     if (t < total) prefetch(t);
;     for (; t < total; t += G) {
;         LAS float* tl = tile + buf * (128 * 65);
; __device__ __forceinline__ void convert_layer(int wv, PP P, int L, int mask, LAS float* tile, int pidx, int pcnt) {
;     ...
;     if (mask & 8) convert_weight(wv, P->w_up + (size_t)L * D * NUP, NUP, D, (bf16_t*)(dob + DO_WUP), D, 0, NUP / 64, P->norm_ffn + L * D, 0, tile, pidx, pcnt);
.LBB0_956:
	s_load_dwordx2 s[10:11], s[10:11], 0x98
	v_lshlrev_b32_e32 v22, 4, v28
	v_and_b32_e32 v22, 0x70, v22
	v_ashrrev_i32_e32 v30, 3, v29
	v_mul_u32_u24_e32 v31, 0x104, v22
	s_waitcnt lgkmcnt(0)
	s_add_u32 s10, s10, 0x5200000
	s_addc_u32 s11, s11, 0
	v_mul_lo_u32 v32, v1, s87
	s_lshl_b32 s19, s16, 6
	s_sub_u32 s98, s48, 64
	s_lshl_b32 s17, s98, 6
	s_mov_b32 s18, 0
	v_lshlrev_b32_e32 v22, 1, v22
	s_waitcnt vmcnt(0)
	s_branch .LBB0_958

; #define LAS __attribute__((address_space(3)))
; __device__ __forceinline__ void lds_barrier() { asm volatile("s_waitcnt lgkmcnt(0)" ::: "memory"); __builtin_amdgcn_s_barrier(); asm volatile("" ::: "memory"); }
; __device__ __forceinline__ void convert_weight(int wv, const float* __restrict__ src, int ldsrc, int Ksrc, bf16_t* dst, int ldd, int koff, int ntn, const float* kscale, int mode, LAS float* tile, int pidx, int pcnt) {
;     ...
;     for (; t < total; t += G) {
;         LAS float* tl = tile + buf * (128 * 65);
; #pragma unroll
;         for (int i = 0; i < 4; ++i) { const int kk = kk0 + i * 32;
;             tl[kk * 65 + n4 + 0] = v[i][0] * ks[i]; tl[kk * 65 + n4 + 1] = v[i][1] * ks[i]; tl[kk * 65 + n4 + 2] = v[i][2] * ks[i]; tl[kk * 65 + n4 + 3] = v[i][3] * ks[i]; }
;         lds_barrier();
;         const int tn = t % ntn, tk = t / ntn; const int n0 = tn * 64, k0 = tk * 128;
;         if (t + G < total) prefetch(t + G);
.LBB0_958:
	s_mul_i32 s12, s18, 0x8200
	s_add_i32 s22, s12, 0
	v_add3_u32 v23, s22, v2, v32
	s_waitcnt vmcnt(2)
	v_pk_mul_f32 v[28:29], v[4:5], v[20:21] op_sel_hi:[1,0]
	ds_write2_b32 v23, v28, v29 offset1:1
	v_pk_mul_f32 v[28:29], v[6:7], v[20:21] op_sel_hi:[1,0]
	ds_write2_b32 v23, v28, v29 offset0:2 offset1:3
	s_waitcnt vmcnt(2)
	v_pk_mul_f32 v[28:29], v[8:9], v[0:1] op_sel_hi:[1,0]
	v_add_u32_e32 v33, 0x2080, v23
	ds_write2_b32 v33, v28, v29 offset1:1
	v_pk_mul_f32 v[28:29], v[10:11], v[0:1] op_sel_hi:[1,0]
	v_add_u32_e32 v33, 0x2088, v23
	ds_write2_b32 v33, v28, v29 offset1:1
	s_waitcnt vmcnt(2)
	v_pk_mul_f32 v[28:29], v[12:13], v[26:27] op_sel_hi:[1,0]
	v_add_u32_e32 v33, 0x4100, v23
	ds_write2_b32 v33, v28, v29 offset1:1
	v_pk_mul_f32 v[28:29], v[14:15], v[26:27] op_sel_hi:[1,0]
	v_add_u32_e32 v33, 0x4108, v23
	ds_write2_b32 v33, v28, v29 offset1:1
	s_waitcnt vmcnt(2)
	v_pk_mul_f32 v[28:29], v[16:17], v[24:25] op_sel_hi:[1,0]
	v_add_u32_e32 v33, 0x6180, v23
	ds_write2_b32 v33, v28, v29 offset1:1
	v_pk_mul_f32 v[28:29], v[18:19], v[24:25] op_sel_hi:[1,0]
	v_add_u32_e32 v23, 0x6188, v23
	ds_write2_b32 v23, v28, v29 offset1:1
	s_waitcnt lgkmcnt(0)
	s_barrier
	s_sub_u32 s98, s48, 64
	s_add_i32 s20, s16, s98
	s_cmpk_gt_i32 s20, 0xaff
	s_cselect_b64 s[12:13], -1, 0
	s_cmpk_lt_i32 s20, 0xb00
	s_mov_b64 s[14:15], -1
	s_cbranch_scc1 .LBB0_960
	s_add_i32 s21, s19, s17
	s_mov_b64 s[14:15], 0
